# adds: SB off-diagonal fast path, indexer MFMA block with separate accumulators, QK phase rescheduled, select_rows<32> next-row score prefetch
# speedup vs baseline: 1.2377x; 1.0068x over previous
; #define LAS __attribute__((address_space(3)))
; #define GAS __attribute__((address_space(1)))
; __device__ __forceinline__ void select_unit(LAS unsigned char* lds, const GAS bf16_t* __restrict__ HA, const GAS float* __restrict__ IW, int b, int qc, GAS float* __restrict__ scr, GAS unsigned long long* __restrict__ MB) {
;     ...
;             for (int i = 0; i < 8; ++i) {
;                 const int kbl = (wid >> 2) + 2 * i, kb = c * 16 + kbl;
;                 if (kb < nkb) {
;                     const LAS bf16_t* kp = Kc + (kbl * 16 + c16) * 72 + lg * 8;
;                     const bf16x8 k0 = *(const LAS bf16x8*)kp, k1 = *(const LAS bf16x8*)(kp + 32);
;                     f32x4 sc = (f32x4){0.f, 0.f, 0.f, 0.f};
; #pragma unroll
;                     for (int hh = 0; hh < 8; ++hh) {
;                         f32x4 acc = __builtin_amdgcn_mfma_f32_16x16x32_bf16(k0, iqf[hh][0], (f32x4){0.f, 0.f, 0.f, 0.f}, 0, 0, 0);
;                         acc = __builtin_amdgcn_mfma_f32_16x16x32_bf16(k1, iqf[hh][1], acc, 0, 0, 0);
; #pragma unroll
;                         for (int r = 0; r < 4; ++r) sc[r] += iwv[hh] * fmaxf(acc[r], 0.f);
;                     }
;                     *(GAS f32x4*)(scr + (size_t)ql * SEQ + kb * 16 + 4 * lg) = sc;
;                 }
.LBB0_360:
	s_cmp_ge_i32 s13, s7
	s_cbranch_scc1 .LBB0_362
	ds_read_b128 v[94:97], v119
	ds_read_b128 v[90:93], v119 offset:64
	s_waitcnt lgkmcnt(1)
	v_mfma_f32_16x16x32_bf16 v[148:151], v[94:97], v[82:85], 0
	v_mfma_f32_16x16x32_bf16 v[156:159], v[94:97], v[30:33], 0
	v_mfma_f32_16x16x32_bf16 v[172:175], v[94:97], v[38:41], 0
	v_mfma_f32_16x16x32_bf16 v[182:185], v[94:97], v[46:49], 0
	v_mfma_f32_16x16x32_bf16 v[186:189], v[94:97], v[54:57], 0
	v_mfma_f32_16x16x32_bf16 v[190:193], v[94:97], v[62:65], 0
	v_mfma_f32_16x16x32_bf16 v[198:201], v[94:97], v[70:73], 0
	v_mfma_f32_16x16x32_bf16 v[202:205], v[94:97], v[78:81], 0
	s_waitcnt lgkmcnt(0)
	v_mfma_f32_16x16x32_bf16 v[148:151], v[90:93], v[26:29], v[148:151]
	v_mfma_f32_16x16x32_bf16 v[156:159], v[90:93], v[34:37], v[156:159]
	v_mfma_f32_16x16x32_bf16 v[172:175], v[90:93], v[42:45], v[172:175]
	v_mfma_f32_16x16x32_bf16 v[182:185], v[90:93], v[50:53], v[182:185]
	v_mfma_f32_16x16x32_bf16 v[186:189], v[90:93], v[58:61], v[186:189]
	v_mfma_f32_16x16x32_bf16 v[190:193], v[90:93], v[66:69], v[190:193]
	v_mfma_f32_16x16x32_bf16 v[198:201], v[90:93], v[74:77], v[198:201]
	v_mfma_f32_16x16x32_bf16 v[202:205], v[90:93], v[86:89], v[202:205]
	s_add_i32 s14, s10, s12
	s_ashr_i32 s15, s14, 31
	v_lshl_add_u64 v[94:95], s[14:15], 2, v[100:101]
	v_max_f32_e32 v148, 0, v148
	v_max_f32_e32 v149, 0, v149
	v_max_f32_e32 v150, 0, v150
	v_max_f32_e32 v151, 0, v151
	v_pk_fma_f32 v[90:91], v[102:103], v[148:149], 0 op_sel_hi:[1,1,0]
	v_pk_fma_f32 v[92:93], v[102:103], v[150:151], 0 op_sel_hi:[1,1,0]
	v_max_f32_e32 v156, 0, v156
	v_max_f32_e32 v157, 0, v157
	v_max_f32_e32 v158, 0, v158
	v_max_f32_e32 v159, 0, v159
	v_pk_fma_f32 v[90:91], v[22:23], v[156:157], v[90:91]
	v_pk_fma_f32 v[92:93], v[22:23], v[158:159], v[92:93]
	v_max_f32_e32 v172, 0, v172
	v_max_f32_e32 v173, 0, v173
	v_max_f32_e32 v174, 0, v174
	v_max_f32_e32 v175, 0, v175
	v_pk_fma_f32 v[90:91], v[104:105], v[172:173], v[90:91]
	v_pk_fma_f32 v[92:93], v[104:105], v[174:175], v[92:93]
	v_max_f32_e32 v182, 0, v182
	v_max_f32_e32 v183, 0, v183
	v_max_f32_e32 v184, 0, v184
	v_max_f32_e32 v185, 0, v185
	v_pk_fma_f32 v[90:91], v[24:25], v[182:183], v[90:91]
	v_pk_fma_f32 v[92:93], v[24:25], v[184:185], v[92:93]
	v_max_f32_e32 v186, 0, v186
	v_max_f32_e32 v187, 0, v187
	v_max_f32_e32 v188, 0, v188
	v_max_f32_e32 v189, 0, v189
	v_pk_fma_f32 v[90:91], v[106:107], v[186:187], v[90:91]
	v_pk_fma_f32 v[92:93], v[106:107], v[188:189], v[92:93]
	v_max_f32_e32 v190, 0, v190
	v_max_f32_e32 v191, 0, v191
	v_max_f32_e32 v192, 0, v192
	v_max_f32_e32 v193, 0, v193
	v_pk_fma_f32 v[90:91], v[18:19], v[190:191], v[90:91]
	v_pk_fma_f32 v[92:93], v[18:19], v[192:193], v[92:93]
	v_max_f32_e32 v198, 0, v198
	v_max_f32_e32 v199, 0, v199
	v_max_f32_e32 v200, 0, v200
	v_max_f32_e32 v201, 0, v201
	v_pk_fma_f32 v[90:91], v[108:109], v[198:199], v[90:91]
	v_pk_fma_f32 v[92:93], v[108:109], v[200:201], v[92:93]
	v_max_f32_e32 v202, 0, v202
	v_max_f32_e32 v203, 0, v203
	v_max_f32_e32 v204, 0, v204
	v_max_f32_e32 v205, 0, v205
	v_pk_fma_f32 v[90:91], v[20:21], v[202:203], v[90:91]
	v_pk_fma_f32 v[92:93], v[20:21], v[204:205], v[92:93]
	global_store_dwordx4 v[94:95], v[90:93], off
.LBB0_362:
	s_add_i32 s14, s13, 2
	s_cmp_ge_i32 s14, s7
	s_cbranch_scc1 .LBB0_359
	ds_read_b128 v[94:97], v119 offset:4608
	ds_read_b128 v[90:93], v119 offset:4672
	s_waitcnt lgkmcnt(1)
	v_mfma_f32_16x16x32_bf16 v[148:151], v[94:97], v[82:85], 0
	v_mfma_f32_16x16x32_bf16 v[156:159], v[94:97], v[30:33], 0
	v_mfma_f32_16x16x32_bf16 v[172:175], v[94:97], v[38:41], 0
	v_mfma_f32_16x16x32_bf16 v[182:185], v[94:97], v[46:49], 0
	v_mfma_f32_16x16x32_bf16 v[186:189], v[94:97], v[54:57], 0
	v_mfma_f32_16x16x32_bf16 v[190:193], v[94:97], v[62:65], 0
	v_mfma_f32_16x16x32_bf16 v[198:201], v[94:97], v[70:73], 0
	v_mfma_f32_16x16x32_bf16 v[202:205], v[94:97], v[78:81], 0
	s_waitcnt lgkmcnt(0)
	v_mfma_f32_16x16x32_bf16 v[148:151], v[90:93], v[26:29], v[148:151]
	v_mfma_f32_16x16x32_bf16 v[156:159], v[90:93], v[34:37], v[156:159]
	v_mfma_f32_16x16x32_bf16 v[172:175], v[90:93], v[42:45], v[172:175]
	v_mfma_f32_16x16x32_bf16 v[182:185], v[90:93], v[50:53], v[182:185]
	v_mfma_f32_16x16x32_bf16 v[186:189], v[90:93], v[58:61], v[186:189]
	v_mfma_f32_16x16x32_bf16 v[190:193], v[90:93], v[66:69], v[190:193]
	v_mfma_f32_16x16x32_bf16 v[198:201], v[90:93], v[74:77], v[198:201]
	v_mfma_f32_16x16x32_bf16 v[202:205], v[90:93], v[86:89], v[202:205]
	s_add_i32 s14, s10, s12
	s_add_i32 s14, s14, 32
	s_ashr_i32 s15, s14, 31
	v_lshl_add_u64 v[94:95], s[14:15], 2, v[100:101]
	v_max_f32_e32 v148, 0, v148
	v_max_f32_e32 v149, 0, v149
	v_max_f32_e32 v150, 0, v150
	v_max_f32_e32 v151, 0, v151
	v_pk_fma_f32 v[90:91], v[102:103], v[148:149], 0 op_sel_hi:[1,1,0]
	v_pk_fma_f32 v[92:93], v[102:103], v[150:151], 0 op_sel_hi:[1,1,0]
	v_max_f32_e32 v156, 0, v156
	v_max_f32_e32 v157, 0, v157
	v_max_f32_e32 v158, 0, v158
	v_max_f32_e32 v159, 0, v159
	v_pk_fma_f32 v[90:91], v[22:23], v[156:157], v[90:91]
	v_pk_fma_f32 v[92:93], v[22:23], v[158:159], v[92:93]
	v_max_f32_e32 v172, 0, v172
	v_max_f32_e32 v173, 0, v173
	v_max_f32_e32 v174, 0, v174
	v_max_f32_e32 v175, 0, v175
	v_pk_fma_f32 v[90:91], v[104:105], v[172:173], v[90:91]
	v_pk_fma_f32 v[92:93], v[104:105], v[174:175], v[92:93]
	v_max_f32_e32 v182, 0, v182
	v_max_f32_e32 v183, 0, v183
	v_max_f32_e32 v184, 0, v184
	v_max_f32_e32 v185, 0, v185
	v_pk_fma_f32 v[90:91], v[24:25], v[182:183], v[90:91]
	v_pk_fma_f32 v[92:93], v[24:25], v[184:185], v[92:93]
	v_max_f32_e32 v186, 0, v186
	v_max_f32_e32 v187, 0, v187
	v_max_f32_e32 v188, 0, v188
	v_max_f32_e32 v189, 0, v189
	v_pk_fma_f32 v[90:91], v[106:107], v[186:187], v[90:91]
	v_pk_fma_f32 v[92:93], v[106:107], v[188:189], v[92:93]
	v_max_f32_e32 v190, 0, v190
	v_max_f32_e32 v191, 0, v191
	v_max_f32_e32 v192, 0, v192
	v_max_f32_e32 v193, 0, v193
	v_pk_fma_f32 v[90:91], v[18:19], v[190:191], v[90:91]
	v_pk_fma_f32 v[92:93], v[18:19], v[192:193], v[92:93]
	v_max_f32_e32 v198, 0, v198
	v_max_f32_e32 v199, 0, v199
	v_max_f32_e32 v200, 0, v200
	v_max_f32_e32 v201, 0, v201
	v_pk_fma_f32 v[90:91], v[108:109], v[198:199], v[90:91]
	v_pk_fma_f32 v[92:93], v[108:109], v[200:201], v[92:93]
	v_max_f32_e32 v202, 0, v202
	v_max_f32_e32 v203, 0, v203
	v_max_f32_e32 v204, 0, v204
	v_max_f32_e32 v205, 0, v205
	v_pk_fma_f32 v[90:91], v[20:21], v[202:203], v[90:91]
	v_pk_fma_f32 v[92:93], v[20:21], v[204:205], v[92:93]
	global_store_dwordx4 v[94:95], v[90:93], off
	s_branch .LBB0_359

; #define LAS __attribute__((address_space(3)))
; #define GAS __attribute__((address_space(1)))
; __device__ __forceinline__ void l1_inv() { __builtin_amdgcn_fence(__ATOMIC_ACQUIRE, "agent"); }
; template <int NJ>
; __device__ __forceinline__ void select_rows(const GAS float* sr0, GAS unsigned long long* mb0, LAS unsigned* hist, LAS unsigned* kbuf, int ntl, int lane) {
;     unsigned vm = ntl >= 32 ? 0xffffffffu : ((1u << ntl) - 1u);
;     asm volatile("" : "+v"(vm));
; #pragma unroll 1
; __device__ __forceinline__ void select_unit(LAS unsigned char* lds, const GAS bf16_t* __restrict__ HA, const GAS float* __restrict__ IW, int b, int qc, GAS float* __restrict__ scr, GAS unsigned long long* __restrict__ MB) {
;     ...
;     asm volatile("s_waitcnt vmcnt(0)" ::: "memory");
;     __syncthreads();
;     l1_inv();
;     GAS unsigned long long* mb0 = MB + (rowbase + qc * 64 + wid * 8) * 32;
;     if (ntl <= 4) {
;         for (int rr = 0; rr < 8; ++rr) if (lane < 32) mb0[rr * 32 + lane] = (lane < ntl) ? ~0ull : 0ull;
;         return;
;     }
;     LAS unsigned* hist = (LAS unsigned*)(lds + 73728) + wid * 384;
;     LAS unsigned* kbuf = (LAS unsigned*)lds + wid * 2048;
;     const GAS float* sr0 = scr + (size_t)(wid * 8) * SEQ + lane;
;     switch ((ntl + 7) >> 3) {
;         case 1: select_rows<8>(sr0, mb0, hist, kbuf, ntl, lane); break;
;         case 2: select_rows<16>(sr0, mb0, hist, kbuf, ntl, lane); break;
;         case 3: select_rows<24>(sr0, mb0, hist, kbuf, ntl, lane); break;
;         default: select_rows<32>(sr0, mb0, hist, kbuf, ntl, lane); break;
;     }
.LBB0_376:
	s_lshl_b32 s0, s4, 3
	s_ashr_i32 s1, s0, 31
	s_add_u32 s2, s5, s0
	s_addc_u32 s3, 0, s1
	s_lshl_b64 s[2:3], s[2:3], 8
	v_readlane_b32 s5, v254, 0
	s_add_u32 s6, s5, s2
	v_readlane_b32 s2, v254, 1
	s_addc_u32 s7, s2, s3
	v_writelane_b32 v254, s6, 10
	s_waitcnt vmcnt(0)
	s_mov_b64 s[2:3], -1
	s_cmp_gt_u32 s23, 3
	v_writelane_b32 v254, s7, 11
	v_cmp_gt_u32_e64 s[6:7], 32, v1
	s_barrier
	s_nop 0
	v_writelane_b32 v254, s6, 12
	s_waitcnt vmcnt(0)
	buffer_inv sc1
	v_writelane_b32 v254, s7, 13
	s_cbranch_scc0 .LBB0_791
	s_mul_i32 s2, s4, 0x600
	s_add_i32 s6, s2, 0
	s_lshl_b32 s2, s4, 13
	s_add_i32 s6, s6, 0x12000
	s_add_i32 s3, s2, 0
	s_lshl_b64 s[0:1], s[0:1], 13
	v_readlane_b32 s4, v254, 2
	v_readlane_b32 s5, v254, 3
	s_add_u32 s0, s4, s0
	s_addc_u32 s1, s5, s1
	v_lshlrev_b32_e32 v6, 2, v1
	v_mov_b32_e32 v7, v0
	v_lshl_add_u64 v[8:9], s[0:1], 0, v[6:7]
	s_add_i32 s0, s23, 8
	s_lshr_b32 s2, s0, 3
	s_lshl_b32 s0, -2, s23
	s_not_b32 s0, s0
	s_cmp_lt_u32 s23, 31
	s_cselect_b32 s0, s0, -1
	v_lshlrev_b64 v[2:3], v1, -1
	v_writelane_b32 v254, s0, 14
	v_lshl_add_u32 v7, v1, 4, s6
	v_cmp_gt_u32_e64 s[74:75], 2, v1
	v_mul_i32_i24_e32 v38, -12, v1
	v_add_u32_e32 v39, s3, v6
	v_not_b32_e32 v40, v3
	v_not_b32_e32 v41, v2
	s_cmp_lt_i32 s2, 2
	s_mov_b64 s[0:1], -1
	s_cbranch_scc1 .LBB0_736
	v_writelane_b32 v254, s74, 15
	s_cmp_lt_i32 s2, 3
	s_nop 0
	v_writelane_b32 v254, s75, 16
	s_cbranch_scc1 .LBB0_649
	s_cmp_lg_u32 s2, 3
	v_cmp_eq_u32_e64 s[2:3], 16, v1
	s_nop 1
	v_writelane_b32 v254, s2, 17
	s_nop 1
	v_writelane_b32 v254, s3, 18
	v_cmp_eq_u32_e64 s[2:3], 17, v1
	s_nop 1
	v_writelane_b32 v254, s2, 19
	s_nop 1
	v_writelane_b32 v254, s3, 20
	v_cmp_eq_u32_e64 s[2:3], 18, v1
	s_nop 1
	v_writelane_b32 v254, s2, 21
	s_nop 1
	v_writelane_b32 v254, s3, 22
	v_cmp_eq_u32_e64 s[2:3], 19, v1
	s_nop 1
	v_writelane_b32 v254, s2, 23
	s_nop 1
	v_writelane_b32 v254, s3, 24
	v_cmp_eq_u32_e64 s[2:3], 20, v1
	s_nop 1
	v_writelane_b32 v254, s2, 25
	s_nop 1
	v_writelane_b32 v254, s3, 26
	v_cmp_eq_u32_e64 s[2:3], 21, v1
	s_nop 1
	v_writelane_b32 v254, s2, 27
	s_nop 1
	v_writelane_b32 v254, s3, 28
	v_cmp_eq_u32_e64 s[2:3], 22, v1
	s_nop 1
	v_writelane_b32 v254, s2, 29
	s_nop 1
	v_writelane_b32 v254, s3, 30
	v_cmp_eq_u32_e64 s[2:3], 23, v1
	s_nop 1
	v_writelane_b32 v254, s2, 31
	s_nop 1
	v_writelane_b32 v254, s3, 32
	s_cbranch_scc0 .LBB0_530
	v_readlane_b32 s0, v254, 14
	s_mov_b32 s12, 0
	s_nop 0
	v_mov_b32_e32 v2, s0
	s_nop 0
	v_and_b32_e32 v3, 1, v2
	v_cmp_eq_u32_e64 s[94:95], 0, v3
	v_and_b32_e32 v3, 2, v2
	v_cmp_eq_u32_e64 s[14:15], 0, v3
	v_and_b32_e32 v3, 4, v2
	v_cmp_eq_u32_e64 s[16:17], 0, v3
	v_and_b32_e32 v3, 8, v2
	v_cmp_eq_u32_e64 s[18:19], 0, v3
	v_and_b32_e32 v3, 16, v2
	v_cmp_eq_u32_e64 s[24:25], 0, v3
	v_and_b32_e32 v3, 32, v2
	v_cmp_eq_u32_e64 s[26:27], 0, v3
	v_and_b32_e32 v3, 64, v2
	v_cmp_eq_u32_e64 s[28:29], 0, v3
	v_and_b32_e32 v3, 0x80, v2
	v_cmp_eq_u32_e64 s[30:31], 0, v3
	v_and_b32_e32 v3, 0x100, v2
	v_cmp_eq_u32_e64 s[34:35], 0, v3
	v_and_b32_e32 v3, 0x200, v2
	v_cmp_eq_u32_e64 s[36:37], 0, v3
	v_and_b32_e32 v3, 0x400, v2
	v_cmp_eq_u32_e64 s[38:39], 0, v3
	v_and_b32_e32 v3, 0x800, v2
	v_cmp_eq_u32_e64 s[40:41], 0, v3
	v_and_b32_e32 v3, 0x1000, v2
	v_cmp_eq_u32_e64 s[42:43], 0, v3
	v_and_b32_e32 v3, 0x2000, v2
	v_cmp_eq_u32_e64 s[44:45], 0, v3
	v_and_b32_e32 v3, 0x4000, v2
	v_cmp_eq_u32_e64 s[46:47], 0, v3
	v_and_b32_e32 v3, 0x8000, v2
	v_cmp_eq_u32_e64 s[48:49], 0, v3
	v_and_b32_e32 v3, 0x10000, v2
	v_cmp_eq_u32_e64 s[50:51], 0, v3
	v_and_b32_e32 v3, 0x20000, v2
	v_cmp_eq_u32_e64 s[52:53], 0, v3
	v_and_b32_e32 v3, 0x40000, v2
	v_cmp_eq_u32_e64 s[54:55], 0, v3
	v_and_b32_e32 v3, 0x80000, v2
	v_cmp_eq_u32_e64 s[64:65], 0, v3
	v_and_b32_e32 v3, 0x100000, v2
	v_cmp_eq_u32_e64 s[66:67], 0, v3
	v_and_b32_e32 v3, 0x200000, v2
	v_cmp_eq_u32_e64 s[70:71], 0, v3
	v_and_b32_e32 v3, 0x400000, v2
	v_cmp_eq_u32_e64 s[72:73], 0, v3
	v_and_b32_e32 v3, 0x800000, v2
	v_cmp_eq_u32_e64 s[76:77], 0, v3
	v_and_b32_e32 v3, 0x1000000, v2
	v_cmp_eq_u32_e64 s[78:79], 0, v3
	v_and_b32_e32 v3, 0x2000000, v2
	v_cmp_eq_u32_e64 s[84:85], 0, v3
	v_and_b32_e32 v3, 0x4000000, v2
	v_cmp_eq_u32_e64 s[90:91], 0, v3
	v_and_b32_e32 v3, 0x8000000, v2
	v_cmp_eq_u32_e64 s[92:93], 0, v3
	v_and_b32_e32 v3, 0x10000000, v2
	v_cmp_eq_u32_e64 s[8:9], 0, v3
	v_and_b32_e32 v3, 0x20000000, v2
	v_cmp_eq_u32_e64 s[0:1], 0, v3
	v_and_b32_e32 v3, 2.0, v2
	s_nop 0
	v_writelane_b32 v254, s0, 33
	s_nop 1
	v_writelane_b32 v254, s1, 34
	v_cmp_eq_u32_e64 s[0:1], 0, v3
	s_nop 1
	v_writelane_b32 v254, s0, 35
	s_nop 1
	v_writelane_b32 v254, s1, 36
	v_cmp_lt_i32_e64 s[0:1], -1, v2
	s_nop 1
	v_writelane_b32 v254, s0, 37
	s_nop 1
	v_writelane_b32 v254, s1, 38
	v_cmp_eq_u32_e64 s[0:1], 63, v1
	s_nop 1
	v_writelane_b32 v254, s0, 41
	s_nop 1
	v_writelane_b32 v254, s1, 42
	v_cmp_gt_u32_e64 s[0:1], 62, v1
	s_nop 1
	v_writelane_b32 v254, s0, 43
	s_nop 1
	v_writelane_b32 v254, s1, 44
	v_cmp_gt_u32_e64 s[0:1], 60, v1
	s_nop 1
	v_writelane_b32 v254, s0, 45
	s_nop 1
	v_writelane_b32 v254, s1, 46
	v_cmp_gt_u32_e64 s[0:1], 56, v1
	s_nop 1
	v_writelane_b32 v254, s0, 47
	s_nop 1
	v_writelane_b32 v254, s1, 48
	v_cmp_gt_u32_e64 s[0:1], 48, v1
	s_nop 1
	v_writelane_b32 v254, s0, 49
	s_nop 1
	v_writelane_b32 v254, s1, 50
	v_cmp_eq_u32_e64 s[0:1], 0, v1
	v_writelane_b32 v254, s94, 59
	s_nop 0
	v_writelane_b32 v255, s0, 23
	v_writelane_b32 v254, s95, 60
	v_writelane_b32 v254, s14, 61
	v_writelane_b32 v255, s1, 24
	v_cmp_eq_u32_e64 s[0:1], 1, v1
	v_writelane_b32 v254, s15, 62
	v_writelane_b32 v254, s16, 63
	v_writelane_b32 v255, s0, 25
	v_writelane_b32 v254, s8, 39
	s_nop 0
	v_writelane_b32 v255, s1, 26
	v_cmp_eq_u32_e64 s[0:1], 2, v1
; #define LAS __attribute__((address_space(3)))
; #define GAS __attribute__((address_space(1)))
; __device__ __forceinline__ unsigned skey_of(float f) { const unsigned u = __float_as_uint(f); return u ^ ((unsigned)((int)u >> 31) | 0x80000000u); }
; template <int NJ>
; __device__ __forceinline__ void select_rows(const GAS float* sr0, GAS unsigned long long* mb0, LAS unsigned* hist, LAS unsigned* kbuf, int ntl, int lane) {
;     unsigned vm = ntl >= 32 ? 0xffffffffu : ((1u << ntl) - 1u);
;     asm volatile("" : "+v"(vm));
; #pragma unroll 1
;     for (int rr = 0; rr < 8; ++rr) {
;         const GAS float* srow = sr0 + (size_t)rr * SEQ;
;         float fv[NJ];
; #pragma unroll
;         for (int j = 0; j < NJ; ++j) fv[j] = srow[64 * j];
;         { unsigned z = 0u; asm volatile("" : "+v"(z));
;           *(LAS u32x4*)(hist + 4 * lane) = (u32x4){z, z, z, z}; if (lane < 2) hist[256 + lane] = z; }
;         __builtin_amdgcn_wave_barrier();
;         unsigned key[NJ];
; #pragma unroll
;         for (int j = 0; j < NJ; ++j) {
;             const float f = fv[j]; const bool ok = (vm >> j) & 1u;
;             key[j] = ok ? skey_of(f) : 0u;
;             const int bk = min(max((int)floorf(f + f) + 128, 0), 255);
;             __hip_atomic_fetch_add(hist + (ok ? bk : 256), 1u, __ATOMIC_RELAXED, __HIP_MEMORY_SCOPE_WORKGROUP);
;         }
;         __builtin_amdgcn_wave_barrier();
;         asm volatile("s_waitcnt lgkmcnt(0)" ::: "memory");
;         unsigned B, rem, C;
;         {
;             const u32x4 hv = *(const LAS u32x4*)(hist + 4 * lane);
;             const unsigned s4 = hv.x + hv.y + hv.z + hv.w;
;             unsigned S = s4;
; #pragma unroll
;             for (int off = 1; off < 64; off <<= 1) { const unsigned n = __shfl_down(S, off); if (lane + off < 64) S += n; }
	v_writelane_b32 v254, s9, 40
	s_nop 0
	v_writelane_b32 v255, s0, 27
	s_nop 1
	v_writelane_b32 v255, s1, 28
	v_cmp_eq_u32_e64 s[0:1], 3, v1
	s_nop 1
	v_writelane_b32 v255, s0, 29
	s_nop 1
	v_writelane_b32 v255, s1, 30
	v_cmp_eq_u32_e64 s[0:1], 4, v1
	s_nop 1
	v_writelane_b32 v255, s0, 31
	s_nop 1
	v_writelane_b32 v255, s1, 32
	v_cmp_eq_u32_e64 s[0:1], 5, v1
	s_nop 1
	v_writelane_b32 v255, s0, 33
	s_nop 1
	v_writelane_b32 v255, s1, 34
	v_cmp_eq_u32_e64 s[0:1], 6, v1
	s_nop 1
	v_writelane_b32 v255, s0, 35
	s_nop 1
	v_writelane_b32 v255, s1, 36
	v_cmp_eq_u32_e64 s[0:1], 7, v1
	s_nop 1
	v_writelane_b32 v255, s0, 37
	s_nop 1
	v_writelane_b32 v255, s1, 38
	v_cmp_eq_u32_e64 s[0:1], 8, v1
	s_nop 1
	v_writelane_b32 v255, s0, 39
	s_nop 1
	v_writelane_b32 v255, s1, 40
	v_cmp_eq_u32_e64 s[0:1], 9, v1
	s_nop 1
	v_writelane_b32 v255, s0, 41
	s_nop 1
	v_writelane_b32 v255, s1, 42
	v_cmp_eq_u32_e64 s[0:1], 10, v1
	s_nop 1
	v_writelane_b32 v255, s0, 43
	s_nop 1
	v_writelane_b32 v255, s1, 44
	v_cmp_eq_u32_e64 s[0:1], 11, v1
	s_nop 1
	v_writelane_b32 v255, s0, 45
	s_nop 1
	v_writelane_b32 v255, s1, 46
	v_cmp_eq_u32_e64 s[0:1], 12, v1
	s_nop 1
	v_writelane_b32 v255, s0, 47
	s_nop 1
	v_writelane_b32 v255, s1, 48
	v_cmp_eq_u32_e64 s[0:1], 13, v1
	s_nop 1
	v_writelane_b32 v255, s0, 49
	s_nop 1
	v_writelane_b32 v255, s1, 50
	v_cmp_eq_u32_e64 s[0:1], 14, v1
	s_nop 1
	v_writelane_b32 v255, s0, 51
	s_nop 1
	v_writelane_b32 v255, s1, 52
	v_cmp_eq_u32_e64 s[0:1], 15, v1
	s_nop 1
	v_writelane_b32 v255, s0, 53
	s_nop 1
	v_writelane_b32 v255, s1, 54
	v_cmp_eq_u32_e64 s[0:1], 24, v1
	s_nop 1
	v_writelane_b32 v255, s0, 55
	s_nop 1
	v_writelane_b32 v255, s1, 56
	v_cmp_eq_u32_e64 s[0:1], 25, v1
	s_nop 1
	v_writelane_b32 v255, s0, 57
	s_nop 1
	v_writelane_b32 v255, s1, 58
	v_cmp_eq_u32_e64 s[0:1], 26, v1
	s_nop 1
	v_writelane_b32 v255, s0, 59
	s_nop 1
	v_writelane_b32 v255, s1, 60
	v_cmp_eq_u32_e64 s[0:1], 27, v1
	s_nop 1
	v_writelane_b32 v255, s0, 61
	s_nop 1
	v_writelane_b32 v255, s1, 62
	v_cmp_eq_u32_e64 s[0:1], 28, v1
	s_nop 1
	v_writelane_b32 v255, s0, 63
	v_writelane_b32 v255, s17, 0
	v_writelane_b32 v255, s18, 1
	v_writelane_b32 v253, s1, 0
	v_cmp_eq_u32_e64 s[0:1], 29, v1
	v_writelane_b32 v255, s19, 2
	v_writelane_b32 v255, s24, 3
	v_writelane_b32 v253, s0, 1
	s_nop 0
	v_writelane_b32 v255, s25, 4
	v_writelane_b32 v253, s1, 2
	v_cmp_eq_u32_e64 s[0:1], 30, v1
	v_writelane_b32 v255, s26, 5
	s_nop 0
	v_writelane_b32 v253, s0, 3
	v_writelane_b32 v255, s27, 6
	v_writelane_b32 v255, s28, 7
	v_writelane_b32 v253, s1, 4
	v_cmp_eq_u32_e64 s[0:1], 31, v1
	v_writelane_b32 v255, s29, 8
	v_writelane_b32 v255, s30, 9
	v_writelane_b32 v253, s0, 5
	s_nop 0
	v_writelane_b32 v255, s31, 10
	v_writelane_b32 v253, s1, 6
	v_writelane_b32 v253, s46, 7
	v_writelane_b32 v255, s34, 11
	s_nop 0
	v_writelane_b32 v253, s47, 8
	v_writelane_b32 v253, s48, 9
	v_writelane_b32 v255, s35, 12
	v_writelane_b32 v255, s36, 13
	v_writelane_b32 v253, s49, 10
	v_writelane_b32 v253, s50, 11
	v_writelane_b32 v255, s37, 14
	v_writelane_b32 v255, s38, 15
	v_writelane_b32 v253, s51, 12
	v_writelane_b32 v253, s52, 13
	v_writelane_b32 v255, s39, 16
	v_writelane_b32 v255, s40, 17
	v_writelane_b32 v253, s53, 14
	v_writelane_b32 v253, s54, 15
	v_writelane_b32 v255, s41, 18
	v_writelane_b32 v255, s42, 19
	v_writelane_b32 v253, s55, 16
	v_writelane_b32 v253, s64, 17
	v_writelane_b32 v255, s43, 20
	v_writelane_b32 v255, s44, 21
	v_writelane_b32 v253, s65, 18
	v_writelane_b32 v253, s66, 19
	v_writelane_b32 v255, s45, 22
	s_nop 0
	v_writelane_b32 v253, s67, 20
	v_writelane_b32 v253, s70, 21
	s_nop 1
	v_writelane_b32 v253, s71, 22
	v_writelane_b32 v253, s72, 23
	s_nop 1
	v_writelane_b32 v253, s73, 24
	v_writelane_b32 v253, s76, 25
	s_nop 1
	v_writelane_b32 v253, s77, 26
	v_writelane_b32 v253, s78, 27
	s_nop 1
	v_writelane_b32 v253, s79, 28
	v_writelane_b32 v253, s84, 29
	s_nop 1
	v_writelane_b32 v253, s85, 30
	v_writelane_b32 v253, s90, 31
	s_nop 1
	v_writelane_b32 v253, s91, 32
	v_writelane_b32 v253, s92, 33
	s_nop 1
	v_writelane_b32 v253, s93, 34
	s_lshl_b32 s88, s12, 11
	v_lshl_add_u64 v[84:85], s[88:89], 2, v[8:9]
	v_add_co_u32_e32 v86, vcc, 0x1000, v84
	s_nop 1
	v_addc_co_u32_e32 v87, vcc, 0, v85, vcc
	global_load_dword v51, v[84:85], off
	global_load_dword v52, v[84:85], off offset:256
	global_load_dword v53, v[84:85], off offset:512
	global_load_dword v54, v[84:85], off offset:768
	global_load_dword v55, v[84:85], off offset:1024
	global_load_dword v56, v[84:85], off offset:1280
	global_load_dword v57, v[84:85], off offset:1536
	global_load_dword v58, v[84:85], off offset:1792
	global_load_dword v59, v[84:85], off offset:2048
	global_load_dword v60, v[84:85], off offset:2304
	global_load_dword v61, v[84:85], off offset:2560
	global_load_dword v62, v[84:85], off offset:2816
	global_load_dword v63, v[84:85], off offset:3072
	global_load_dword v64, v[84:85], off offset:3328
	global_load_dword v65, v[84:85], off offset:3584
	global_load_dword v66, v[84:85], off offset:3840
	global_load_dword v67, v[86:87], off
	global_load_dword v68, v[86:87], off offset:256
	global_load_dword v69, v[86:87], off offset:512
	global_load_dword v70, v[86:87], off offset:768
	global_load_dword v71, v[86:87], off offset:1024
	global_load_dword v72, v[86:87], off offset:1280
	global_load_dword v73, v[86:87], off offset:1536
	global_load_dword v74, v[86:87], off offset:1792
	global_load_dword v75, v[86:87], off offset:2048
	global_load_dword v76, v[86:87], off offset:2304
	global_load_dword v77, v[86:87], off offset:2560
	global_load_dword v78, v[86:87], off offset:2816
	global_load_dword v79, v[86:87], off offset:3072
	global_load_dword v80, v[86:87], off offset:3328
	global_load_dword v81, v[86:87], off offset:3584
	global_load_dword v82, v[86:87], off offset:3840
	global_load_dword v83, v[84:85], off
	s_branch .LBB0_382

; #define LAS __attribute__((address_space(3)))
; #define GAS __attribute__((address_space(1)))
; __device__ __forceinline__ unsigned skey_of(float f) { const unsigned u = __float_as_uint(f); return u ^ ((unsigned)((int)u >> 31) | 0x80000000u); }
; template <int NJ>
; __device__ __forceinline__ void select_rows(const GAS float* sr0, GAS unsigned long long* mb0, LAS unsigned* hist, LAS unsigned* kbuf, int ntl, int lane) {
;     ...
;     for (int rr = 0; rr < 8; ++rr) {
;         const GAS float* srow = sr0 + (size_t)rr * SEQ;
;         float fv[NJ];
; #pragma unroll
;         for (int j = 0; j < NJ; ++j) fv[j] = srow[64 * j];
;         { unsigned z = 0u; asm volatile("" : "+v"(z));
;           *(LAS u32x4*)(hist + 4 * lane) = (u32x4){z, z, z, z}; if (lane < 2) hist[256 + lane] = z; }
;         __builtin_amdgcn_wave_barrier();
;         unsigned key[NJ];
; #pragma unroll
;         for (int j = 0; j < NJ; ++j) {
;             const float f = fv[j]; const bool ok = (vm >> j) & 1u;
;             key[j] = ok ? skey_of(f) : 0u;
;             const int bk = min(max((int)floorf(f + f) + 128, 0), 255);
;             __hip_atomic_fetch_add(hist + (ok ? bk : 256), 1u, __ATOMIC_RELAXED, __HIP_MEMORY_SCOPE_WORKGROUP);
;         }
.LBB0_382:
	s_lshl_b32 s88, s12, 11
	v_lshl_add_u64 v[2:3], s[88:89], 2, v[8:9]
	s_movk_i32 s0, 0x1000
	s_add_i32 s98, s88, 0x800
	s_mov_b32 s99, s89
	s_waitcnt vmcnt(1)
	v_mov_b32_e32 v45, v51
	v_mov_b32_e32 v10, v52
	v_mov_b32_e32 v11, v53
	v_mov_b32_e32 v12, v54
	v_mov_b32_e32 v13, v55
	v_mov_b32_e32 v14, v56
	v_mov_b32_e32 v15, v57
	v_mov_b32_e32 v16, v58
	v_mov_b32_e32 v17, v59
	v_mov_b32_e32 v18, v60
	v_mov_b32_e32 v19, v61
	v_mov_b32_e32 v20, v62
	v_mov_b32_e32 v21, v63
	v_mov_b32_e32 v22, v64
	v_mov_b32_e32 v23, v65
	v_mov_b32_e32 v24, v66
	v_mov_b32_e32 v25, v67
	v_mov_b32_e32 v26, v68
	v_mov_b32_e32 v27, v69
	v_mov_b32_e32 v28, v70
	v_mov_b32_e32 v29, v71
	v_mov_b32_e32 v30, v72
	v_mov_b32_e32 v31, v73
	v_mov_b32_e32 v32, v74
	v_mov_b32_e32 v33, v75
	v_mov_b32_e32 v34, v76
	v_mov_b32_e32 v35, v77
	v_mov_b32_e32 v36, v78
	v_mov_b32_e32 v37, v79
	v_mov_b32_e32 v42, v80
	v_mov_b32_e32 v43, v81
	v_mov_b32_e32 v44, v82
	v_lshl_add_u64 v[84:85], s[98:99], 2, v[8:9]
	v_add_co_u32_e32 v86, vcc, 0x1000, v84
	s_nop 1
	v_addc_co_u32_e32 v87, vcc, 0, v85, vcc
	global_load_dword v51, v[84:85], off
	global_load_dword v52, v[84:85], off offset:256
	global_load_dword v53, v[84:85], off offset:512
	global_load_dword v54, v[84:85], off offset:768
	global_load_dword v55, v[84:85], off offset:1024
	global_load_dword v56, v[84:85], off offset:1280
	global_load_dword v57, v[84:85], off offset:1536
	global_load_dword v58, v[84:85], off offset:1792
	global_load_dword v59, v[84:85], off offset:2048
	global_load_dword v60, v[84:85], off offset:2304
	global_load_dword v61, v[84:85], off offset:2560
	global_load_dword v62, v[84:85], off offset:2816
	global_load_dword v63, v[84:85], off offset:3072
	global_load_dword v64, v[84:85], off offset:3328
	global_load_dword v65, v[84:85], off offset:3584
	global_load_dword v66, v[84:85], off offset:3840
	global_load_dword v67, v[86:87], off
	global_load_dword v68, v[86:87], off offset:256
	global_load_dword v69, v[86:87], off offset:512
	global_load_dword v70, v[86:87], off offset:768
	global_load_dword v71, v[86:87], off offset:1024
	global_load_dword v72, v[86:87], off offset:1280
	global_load_dword v73, v[86:87], off offset:1536
	global_load_dword v74, v[86:87], off offset:1792
	global_load_dword v75, v[86:87], off offset:2048
	global_load_dword v76, v[86:87], off offset:2304
	global_load_dword v77, v[86:87], off offset:2560
	global_load_dword v78, v[86:87], off offset:2816
	global_load_dword v79, v[86:87], off offset:3072
	global_load_dword v80, v[86:87], off offset:3328
	global_load_dword v81, v[86:87], off offset:3584
	global_load_dword v82, v[86:87], off offset:3840
	v_mov_b32_e32 v2, 0
	s_nop 0
	v_mov_b32_e32 v3, v2
	v_mov_b32_e32 v4, v2
	v_mov_b32_e32 v5, v2
	ds_write_b128 v7, v[2:5]
	s_and_saveexec_b64 s[0:1], s[74:75]
	v_add_u32_e32 v3, v7, v38
	ds_write_b32 v3, v2 offset:1024
	s_or_b64 exec, exec, s[0:1]
	v_add_f32_e32 v2, v45, v45
	v_floor_f32_e32 v2, v2
	v_cvt_i32_f32_e32 v2, v2
	v_add_f32_e32 v3, v10, v10
	v_floor_f32_e32 v3, v3
	v_cvt_i32_f32_e32 v3, v3
	v_max_i32_e32 v2, 0xffffff80, v2
	v_add_u32_e32 v2, 0x80, v2
	v_min_u32_e32 v2, 0xff, v2
	v_cndmask_b32_e64 v2, v2, v226, s[94:95]
	v_lshl_add_u32 v2, v2, 2, s6
	ds_add_u32 v2, v223
	v_max_i32_e32 v2, 0xffffff80, v3
	v_add_f32_e32 v3, v11, v11
	v_floor_f32_e32 v3, v3
	v_add_u32_e32 v2, 0x80, v2
	v_cvt_i32_f32_e32 v3, v3
	v_min_u32_e32 v2, 0xff, v2
	v_cndmask_b32_e64 v2, v2, v226, s[14:15]
	v_lshl_add_u32 v2, v2, 2, s6
	ds_add_u32 v2, v223
	v_max_i32_e32 v2, 0xffffff80, v3
	v_add_f32_e32 v3, v12, v12
	v_floor_f32_e32 v3, v3
	v_add_u32_e32 v2, 0x80, v2
	v_cvt_i32_f32_e32 v3, v3
	v_min_u32_e32 v2, 0xff, v2
	v_cndmask_b32_e64 v2, v2, v226, s[16:17]
	v_lshl_add_u32 v2, v2, 2, s6
	ds_add_u32 v2, v223
	v_max_i32_e32 v2, 0xffffff80, v3
	v_add_f32_e32 v3, v13, v13
	v_floor_f32_e32 v3, v3
	v_add_u32_e32 v2, 0x80, v2
	v_cvt_i32_f32_e32 v3, v3
	v_min_u32_e32 v2, 0xff, v2
	v_cndmask_b32_e64 v2, v2, v226, s[18:19]
	v_lshl_add_u32 v2, v2, 2, s6
	ds_add_u32 v2, v223
	v_max_i32_e32 v2, 0xffffff80, v3
	v_add_f32_e32 v3, v14, v14
	v_floor_f32_e32 v3, v3
	v_add_u32_e32 v2, 0x80, v2
	v_cvt_i32_f32_e32 v3, v3
	v_min_u32_e32 v2, 0xff, v2
	v_cndmask_b32_e64 v2, v2, v226, s[24:25]
	v_lshl_add_u32 v2, v2, 2, s6
	ds_add_u32 v2, v223
	v_max_i32_e32 v2, 0xffffff80, v3
	v_add_f32_e32 v3, v15, v15
	v_floor_f32_e32 v3, v3
	v_add_u32_e32 v2, 0x80, v2
	v_cvt_i32_f32_e32 v3, v3
	v_min_u32_e32 v2, 0xff, v2
	v_cndmask_b32_e64 v2, v2, v226, s[26:27]
	v_lshl_add_u32 v2, v2, 2, s6
	ds_add_u32 v2, v223
	v_max_i32_e32 v2, 0xffffff80, v3
	v_add_f32_e32 v3, v16, v16
	v_floor_f32_e32 v3, v3
	v_add_u32_e32 v2, 0x80, v2
	v_cvt_i32_f32_e32 v3, v3
	v_min_u32_e32 v2, 0xff, v2
	v_cndmask_b32_e64 v2, v2, v226, s[28:29]
	v_lshl_add_u32 v2, v2, 2, s6
	ds_add_u32 v2, v223
	v_max_i32_e32 v2, 0xffffff80, v3
	v_add_f32_e32 v3, v17, v17
	v_floor_f32_e32 v3, v3
	v_add_u32_e32 v2, 0x80, v2
	v_cvt_i32_f32_e32 v3, v3
	v_min_u32_e32 v2, 0xff, v2
	v_cndmask_b32_e64 v2, v2, v226, s[30:31]
	v_lshl_add_u32 v2, v2, 2, s6
	ds_add_u32 v2, v223
	v_max_i32_e32 v2, 0xffffff80, v3
	v_add_f32_e32 v3, v18, v18
	v_floor_f32_e32 v3, v3
	v_add_u32_e32 v2, 0x80, v2
	v_cvt_i32_f32_e32 v3, v3
	v_min_u32_e32 v2, 0xff, v2
	v_cndmask_b32_e64 v2, v2, v226, s[34:35]
	v_lshl_add_u32 v2, v2, 2, s6
	ds_add_u32 v2, v223
	v_max_i32_e32 v2, 0xffffff80, v3
	v_add_f32_e32 v3, v19, v19
	v_floor_f32_e32 v3, v3
	v_add_u32_e32 v2, 0x80, v2
	v_cvt_i32_f32_e32 v3, v3
	v_min_u32_e32 v2, 0xff, v2
	v_cndmask_b32_e64 v2, v2, v226, s[36:37]
	v_lshl_add_u32 v2, v2, 2, s6
	ds_add_u32 v2, v223
	v_max_i32_e32 v2, 0xffffff80, v3
	v_add_f32_e32 v3, v20, v20
; __device__ __forceinline__ unsigned skey_of(float f) { const unsigned u = __float_as_uint(f); return u ^ ((unsigned)((int)u >> 31) | 0x80000000u); }
; template <int NJ>
; __device__ __forceinline__ void select_rows(const GAS float* sr0, GAS unsigned long long* mb0, LAS unsigned* hist, LAS unsigned* kbuf, int ntl, int lane) {
;     ...
; #pragma unroll
;         for (int j = 0; j < NJ; ++j) {
;             const float f = fv[j]; const bool ok = (vm >> j) & 1u;
;             key[j] = ok ? skey_of(f) : 0u;
;             const int bk = min(max((int)floorf(f + f) + 128, 0), 255);
;             __hip_atomic_fetch_add(hist + (ok ? bk : 256), 1u, __ATOMIC_RELAXED, __HIP_MEMORY_SCOPE_WORKGROUP);
;         }
	v_floor_f32_e32 v3, v3
	v_add_u32_e32 v2, 0x80, v2
	v_cvt_i32_f32_e32 v3, v3
	v_min_u32_e32 v2, 0xff, v2
	v_cndmask_b32_e64 v2, v2, v226, s[38:39]
	v_lshl_add_u32 v2, v2, 2, s6
	ds_add_u32 v2, v223
	v_max_i32_e32 v2, 0xffffff80, v3
	v_add_f32_e32 v3, v21, v21
	v_floor_f32_e32 v3, v3
	v_add_u32_e32 v2, 0x80, v2
	v_cvt_i32_f32_e32 v3, v3
	v_min_u32_e32 v2, 0xff, v2
	v_cndmask_b32_e64 v2, v2, v226, s[40:41]
	v_lshl_add_u32 v2, v2, 2, s6
	ds_add_u32 v2, v223
	v_max_i32_e32 v2, 0xffffff80, v3
	v_add_f32_e32 v3, v22, v22
	v_floor_f32_e32 v3, v3
	v_add_u32_e32 v2, 0x80, v2
	v_cvt_i32_f32_e32 v3, v3
	v_min_u32_e32 v2, 0xff, v2
	v_cndmask_b32_e64 v2, v2, v226, s[42:43]
	v_lshl_add_u32 v2, v2, 2, s6
	ds_add_u32 v2, v223
	v_max_i32_e32 v2, 0xffffff80, v3
	v_add_f32_e32 v3, v23, v23
	v_floor_f32_e32 v3, v3
	v_add_u32_e32 v2, 0x80, v2
	v_cvt_i32_f32_e32 v3, v3
	v_min_u32_e32 v2, 0xff, v2
	v_cndmask_b32_e64 v2, v2, v226, s[44:45]
	v_lshl_add_u32 v2, v2, 2, s6
	ds_add_u32 v2, v223
	v_max_i32_e32 v2, 0xffffff80, v3
	v_add_f32_e32 v3, v24, v24
	v_floor_f32_e32 v3, v3
	v_add_u32_e32 v2, 0x80, v2
	v_cvt_i32_f32_e32 v3, v3
	v_min_u32_e32 v2, 0xff, v2
	v_cndmask_b32_e64 v2, v2, v226, s[46:47]
	v_lshl_add_u32 v2, v2, 2, s6
	ds_add_u32 v2, v223
	v_max_i32_e32 v2, 0xffffff80, v3
	v_add_f32_e32 v3, v25, v25
	v_floor_f32_e32 v3, v3
	v_add_u32_e32 v2, 0x80, v2
	v_cvt_i32_f32_e32 v3, v3
	v_min_u32_e32 v2, 0xff, v2
	v_cndmask_b32_e64 v2, v2, v226, s[48:49]
	v_lshl_add_u32 v2, v2, 2, s6
	ds_add_u32 v2, v223
	v_max_i32_e32 v2, 0xffffff80, v3
	v_add_f32_e32 v3, v26, v26
	v_floor_f32_e32 v3, v3
	v_add_u32_e32 v2, 0x80, v2
	v_cvt_i32_f32_e32 v3, v3
	v_min_u32_e32 v2, 0xff, v2
	v_cndmask_b32_e64 v2, v2, v226, s[50:51]
	v_lshl_add_u32 v2, v2, 2, s6
	ds_add_u32 v2, v223
	v_max_i32_e32 v2, 0xffffff80, v3
	v_add_f32_e32 v3, v27, v27
	v_floor_f32_e32 v3, v3
	v_add_u32_e32 v2, 0x80, v2
	v_cvt_i32_f32_e32 v3, v3
	v_min_u32_e32 v2, 0xff, v2
	v_cndmask_b32_e64 v2, v2, v226, s[52:53]
	v_lshl_add_u32 v2, v2, 2, s6
	ds_add_u32 v2, v223
	v_max_i32_e32 v2, 0xffffff80, v3
	v_add_f32_e32 v3, v28, v28
	v_floor_f32_e32 v3, v3
	v_add_u32_e32 v2, 0x80, v2
	v_cvt_i32_f32_e32 v3, v3
	v_min_u32_e32 v2, 0xff, v2
	v_cndmask_b32_e64 v2, v2, v226, s[54:55]
	v_lshl_add_u32 v2, v2, 2, s6
	ds_add_u32 v2, v223
	v_max_i32_e32 v2, 0xffffff80, v3
	v_add_f32_e32 v3, v29, v29
	v_floor_f32_e32 v3, v3
	v_add_u32_e32 v2, 0x80, v2
	v_cvt_i32_f32_e32 v3, v3
	v_min_u32_e32 v2, 0xff, v2
	v_cndmask_b32_e64 v2, v2, v226, s[64:65]
	v_lshl_add_u32 v2, v2, 2, s6
	ds_add_u32 v2, v223
	v_max_i32_e32 v2, 0xffffff80, v3
	v_add_f32_e32 v3, v30, v30
	v_floor_f32_e32 v3, v3
	v_add_u32_e32 v2, 0x80, v2
	v_cvt_i32_f32_e32 v3, v3
	v_min_u32_e32 v2, 0xff, v2
	v_cndmask_b32_e64 v2, v2, v226, s[66:67]
	v_lshl_add_u32 v2, v2, 2, s6
	ds_add_u32 v2, v223
	v_max_i32_e32 v2, 0xffffff80, v3
	v_add_f32_e32 v3, v31, v31
	v_floor_f32_e32 v3, v3
	v_add_u32_e32 v2, 0x80, v2
	v_cvt_i32_f32_e32 v3, v3
	v_min_u32_e32 v2, 0xff, v2
	v_cndmask_b32_e64 v2, v2, v226, s[70:71]
	v_lshl_add_u32 v2, v2, 2, s6
	ds_add_u32 v2, v223
	v_max_i32_e32 v2, 0xffffff80, v3
	v_add_f32_e32 v3, v32, v32
	v_floor_f32_e32 v3, v3
	v_add_u32_e32 v2, 0x80, v2
	v_cvt_i32_f32_e32 v3, v3
	v_min_u32_e32 v2, 0xff, v2
	v_cndmask_b32_e64 v2, v2, v226, s[72:73]
	v_lshl_add_u32 v2, v2, 2, s6
	ds_add_u32 v2, v223
	v_max_i32_e32 v2, 0xffffff80, v3
	v_add_f32_e32 v3, v33, v33
	v_floor_f32_e32 v3, v3
	v_add_u32_e32 v2, 0x80, v2
	v_cvt_i32_f32_e32 v3, v3
	v_min_u32_e32 v2, 0xff, v2
	v_cndmask_b32_e64 v2, v2, v226, s[76:77]
	v_lshl_add_u32 v2, v2, 2, s6
	ds_add_u32 v2, v223
	v_max_i32_e32 v2, 0xffffff80, v3
	v_add_f32_e32 v3, v34, v34
	v_floor_f32_e32 v3, v3
	v_add_u32_e32 v2, 0x80, v2
	v_cvt_i32_f32_e32 v3, v3
	v_min_u32_e32 v2, 0xff, v2
	v_cndmask_b32_e64 v2, v2, v226, s[78:79]
	v_lshl_add_u32 v2, v2, 2, s6
	ds_add_u32 v2, v223
	v_max_i32_e32 v2, 0xffffff80, v3
	v_add_f32_e32 v3, v35, v35
	v_floor_f32_e32 v3, v3
	v_add_u32_e32 v2, 0x80, v2
	v_cvt_i32_f32_e32 v3, v3
	v_min_u32_e32 v2, 0xff, v2
	v_cndmask_b32_e64 v2, v2, v226, s[84:85]
	v_lshl_add_u32 v2, v2, 2, s6
	ds_add_u32 v2, v223
	v_max_i32_e32 v2, 0xffffff80, v3
	v_add_f32_e32 v3, v36, v36
	v_floor_f32_e32 v3, v3
	v_add_u32_e32 v2, 0x80, v2
	v_cvt_i32_f32_e32 v3, v3
	v_min_u32_e32 v2, 0xff, v2
	v_cndmask_b32_e64 v2, v2, v226, s[90:91]
	v_lshl_add_u32 v2, v2, 2, s6
	ds_add_u32 v2, v223
	v_max_i32_e32 v2, 0xffffff80, v3
	v_add_f32_e32 v3, v37, v37
	v_floor_f32_e32 v3, v3
	v_add_u32_e32 v2, 0x80, v2
	v_cvt_i32_f32_e32 v3, v3
	v_min_u32_e32 v2, 0xff, v2
	v_cndmask_b32_e64 v2, v2, v226, s[92:93]
	v_lshl_add_u32 v2, v2, 2, s6
	ds_add_u32 v2, v223
	v_max_i32_e32 v2, 0xffffff80, v3
	v_add_f32_e32 v3, v42, v42
	v_floor_f32_e32 v3, v3
	v_add_u32_e32 v2, 0x80, v2
	v_cvt_i32_f32_e32 v3, v3
	v_min_u32_e32 v2, 0xff, v2
	v_cndmask_b32_e64 v2, v2, v226, s[8:9]
	v_lshl_add_u32 v2, v2, 2, s6
	ds_add_u32 v2, v223
	v_max_i32_e32 v2, 0xffffff80, v3
	v_add_f32_e32 v3, v43, v43
	v_floor_f32_e32 v3, v3
	v_add_u32_e32 v2, 0x80, v2
	v_cvt_i32_f32_e32 v3, v3
	v_readlane_b32 s0, v254, 33
	v_min_u32_e32 v2, 0xff, v2
	v_readlane_b32 s1, v254, 34
	s_nop 1
	v_cndmask_b32_e64 v2, v2, v226, s[0:1]
	v_lshl_add_u32 v2, v2, 2, s6
	ds_add_u32 v2, v223
	v_max_i32_e32 v2, 0xffffff80, v3
	v_add_f32_e32 v3, v44, v44
	v_floor_f32_e32 v3, v3
	v_add_u32_e32 v2, 0x80, v2
	v_cvt_i32_f32_e32 v3, v3
	v_readlane_b32 s0, v254, 35
	v_min_u32_e32 v2, 0xff, v2
	v_readlane_b32 s1, v254, 36
	s_nop 1
	v_cndmask_b32_e64 v2, v2, v226, s[0:1]
	v_lshl_add_u32 v2, v2, 2, s6
	ds_add_u32 v2, v223
	v_max_i32_e32 v2, 0xffffff80, v3
	v_add_u32_e32 v2, 0x80, v2
	v_readlane_b32 s0, v254, 37
	v_min_u32_e32 v2, 0xff, v2
	v_readlane_b32 s1, v254, 38
	s_nop 1
	v_cndmask_b32_e64 v2, v2, v226, s[0:1]
	v_lshl_add_u32 v2, v2, 2, s6
	ds_add_u32 v2, v223
	s_waitcnt lgkmcnt(0)
; #define LAS __attribute__((address_space(3)))
; template <int NJ>
; __device__ __forceinline__ void select_rows(const GAS float* sr0, GAS unsigned long long* mb0, LAS unsigned* hist, LAS unsigned* kbuf, int ntl, int lane) {
;     ...
;         {
;             const u32x4 hv = *(const LAS u32x4*)(hist + 4 * lane);
;             const unsigned s4 = hv.x + hv.y + hv.z + hv.w;
;             unsigned S = s4;
; #pragma unroll
;             for (int off = 1; off < 64; off <<= 1) { const unsigned n = __shfl_down(S, off); if (lane + off < 64) S += n; }
;             const unsigned excl = S - s4;
;             const bool mine = (excl < 256u) && (256u <= S);
;             unsigned dl, above, cnt, c = excl;
;             if (c + hv.w >= 256u) { dl = 3; above = c; cnt = hv.w; } else { c += hv.w; if (c + hv.z >= 256u) { dl = 2; above = c; cnt = hv.z; } else { c += hv.z; if (c + hv.y >= 256u) { dl = 1; above = c; cnt = hv.y; } else { c += hv.y; dl = 0; above = c; cnt = hv.x; } } }
;             const unsigned long long bm = __ballot(mine);
;             const int src = bm ? (int)__builtin_ctzll(bm) : 0;
;             B = (unsigned)__builtin_amdgcn_readlane((int)(4 * lane + dl), src);
;             rem = 256u - (unsigned)__builtin_amdgcn_readlane((int)above, src);
;             C = (unsigned)__builtin_amdgcn_readlane((int)cnt, src);
	ds_read_b128 v[2:5], v7
	v_readlane_b32 s0, v254, 41
	v_readlane_b32 s1, v254, 42
	s_waitcnt lgkmcnt(0)
	v_add_u32_e32 v46, v2, v3
	v_add3_u32 v47, v46, v4, v5
	v_and_b32_e32 v46, 63, v224
	v_cmp_ne_u32_e32 vcc, 63, v46
	s_nop 1
	v_addc_co_u32_e32 v48, vcc, 0, v224, vcc
	v_lshlrev_b32_e32 v48, 2, v48
	ds_bpermute_b32 v48, v48, v47
	v_cmp_gt_u32_e32 vcc, 62, v46
	s_waitcnt lgkmcnt(0)
	v_cndmask_b32_e64 v48, v48, 0, s[0:1]
	v_cndmask_b32_e64 v49, 0, 2, vcc
	v_add_u32_e32 v48, v47, v48
	v_add_lshl_u32 v49, v49, v224, 2
	ds_bpermute_b32 v49, v49, v48
	v_readlane_b32 s0, v254, 43
	v_readlane_b32 s1, v254, 44
	v_cmp_gt_u32_e32 vcc, 60, v46
	s_waitcnt lgkmcnt(0)
	v_cndmask_b32_e64 v49, 0, v49, s[0:1]
	v_add_u32_e32 v48, v48, v49
	v_cndmask_b32_e64 v49, 0, 4, vcc
	v_add_lshl_u32 v49, v49, v224, 2
	ds_bpermute_b32 v49, v49, v48
	v_readlane_b32 s0, v254, 45
	v_readlane_b32 s1, v254, 46
	v_cmp_gt_u32_e32 vcc, 56, v46
	s_waitcnt lgkmcnt(0)
	v_cndmask_b32_e64 v49, 0, v49, s[0:1]
	v_add_u32_e32 v48, v48, v49
	v_cndmask_b32_e64 v49, 0, 8, vcc
	v_add_lshl_u32 v49, v49, v224, 2
	ds_bpermute_b32 v49, v49, v48
	v_readlane_b32 s0, v254, 47
	v_readlane_b32 s1, v254, 48
	v_cmp_gt_u32_e32 vcc, 48, v46
	s_waitcnt lgkmcnt(0)
	v_cndmask_b32_e64 v49, 0, v49, s[0:1]
	v_cndmask_b32_e64 v46, 0, 16, vcc
	v_add_u32_e32 v48, v48, v49
	v_add_lshl_u32 v46, v46, v224, 2
	ds_bpermute_b32 v46, v46, v48
	v_readlane_b32 s0, v254, 49
	v_readlane_b32 s1, v254, 50
	s_waitcnt lgkmcnt(0)
	s_nop 0
	v_cndmask_b32_e64 v46, 0, v46, s[0:1]
	v_add_u32_e32 v46, v48, v46
	ds_bpermute_b32 v48, v225, v46
	v_readlane_b32 s0, v254, 12
	v_readlane_b32 s1, v254, 13
	s_waitcnt lgkmcnt(0)
	s_nop 0
	v_cndmask_b32_e64 v48, 0, v48, s[0:1]
	v_add_u32_e32 v46, v46, v48
	v_sub_u32_e32 v47, v46, v47
	v_add_u32_e32 v50, v47, v5
	v_cmp_gt_u32_e32 vcc, s63, v50
	v_mov_b32_e32 v48, 3
	v_mov_b32_e32 v49, v47
	s_and_saveexec_b64 s[0:1], vcc
	s_cbranch_execz .LBB0_388
	v_add_u32_e32 v5, v50, v4
	v_cmp_gt_u32_e32 vcc, s63, v5
	v_mov_b32_e32 v48, 2
	s_and_saveexec_b64 s[2:3], vcc
	v_add_u32_e32 v4, v5, v3
	s_movk_i32 s4, 0xff
	v_cmp_lt_u32_e32 vcc, s4, v4
	s_nop 1
	v_cndmask_b32_e64 v48, 0, 1, vcc
	v_cndmask_b32_e32 v50, v4, v5, vcc
	v_cndmask_b32_e32 v4, v2, v3, vcc
	s_or_b64 exec, exec, s[2:3]
	v_mov_b32_e32 v5, v4
	v_mov_b32_e32 v49, v50

.LBB0_803:
	s_add_i32 s4, s6, s13
	s_cmp_lt_i32 s4, 0
	s_cbranch_scc1 .LBB0_807
	s_mul_hi_u32 s4, s12, 0xcccccccd
	s_lshr_b32 s4, s4, 2
	s_mul_i32 s4, s4, 0x16800
	v_subrev_u32_e32 v34, s4, v150
	s_add_i32 s15, s10, s7
	v_add_u32_e32 v74, s15, v34
	ds_read_b128 v[34:37], v74 offset:4608
	ds_read_b128 v[38:41], v74
	ds_read_b128 v[66:69], v74 offset:32
	ds_read_b128 v[70:73], v74 offset:4640
	s_cmp_lg_u32 s13, 0
	s_waitcnt lgkmcnt(2)
	v_mfma_f32_32x32x16_bf16 v[50:65], v[38:41], v[90:93], 0
	v_subrev_u32_e32 v1, s4, v132
	v_subrev_u32_e32 v152, s4, v133
	v_subrev_u32_e32 v153, s4, v134
	v_subrev_u32_e32 v154, s4, v135
	v_subrev_u32_e32 v155, s4, v136
	v_subrev_u32_e32 v156, s4, v137
	v_subrev_u32_e32 v157, s4, v138
	v_mfma_f32_32x32x16_bf16 v[34:49], v[34:37], v[90:93], 0
	v_subrev_u32_e32 v158, s4, v139
	v_subrev_u32_e32 v159, s4, v140
	v_subrev_u32_e32 v160, s4, v141
	v_subrev_u32_e32 v161, s4, v142
	v_subrev_u32_e32 v162, s4, v143
	v_subrev_u32_e32 v163, s4, v144
	v_subrev_u32_e32 v164, s4, v145
	s_waitcnt lgkmcnt(1)
	v_mfma_f32_32x32x16_bf16 v[50:65], v[66:69], v[94:97], v[50:65]
	v_subrev_u32_e32 v165, s4, v146
	v_subrev_u32_e32 v166, s4, v147
	s_cselect_b64 s[4:5], -1, 0
	v_readlane_b32 s16, v252, 30
	v_readlane_b32 s18, v252, 32
	v_readlane_b32 s19, v252, 33
	v_readlane_b32 s17, v252, 31
	s_waitcnt lgkmcnt(0)
	v_mfma_f32_32x32x16_bf16 v[34:49], v[70:73], v[94:97], v[34:49]
	ds_read_b128 v[66:69], v74 offset:64
	ds_read_b128 v[70:73], v74 offset:4672
	s_mov_b32 s18, s16
	s_mov_b32 s19, s16
	s_mov_b32 s17, s16
	v_mov_b64_e32 v[120:121], s[18:19]
	v_mov_b64_e32 v[118:119], s[16:17]
	v_add_u32_e32 v1, s15, v1
	s_waitcnt lgkmcnt(1)
	v_mfma_f32_32x32x16_bf16 v[50:65], v[66:69], v[98:101], v[50:65]
	s_waitcnt lgkmcnt(0)
	v_mfma_f32_32x32x16_bf16 v[34:49], v[70:73], v[98:101], v[34:49]
	ds_read_b128 v[66:69], v74 offset:96
	ds_read_b128 v[70:73], v74 offset:4704
	s_waitcnt lgkmcnt(1)
	v_mfma_f32_32x32x16_bf16 v[50:65], v[66:69], v[102:105], v[50:65]
	v_subrev_u32_e32 v66, 59, v149
	v_cmp_lt_i32_e32 vcc, v66, v130
	s_or_b64 vcc, s[4:5], vcc
	s_waitcnt lgkmcnt(0)
	v_mfma_f32_32x32x16_bf16 v[34:49], v[70:73], v[102:105], v[34:49]
	s_cmp_lg_u64 s[4:5], 0
	s_cbranch_scc1 .Lsb_fast
	s_nop 6
	v_exp_f32_e64 v68, -|v50|
	v_max_f32_e32 v67, v50, v50
	v_max_f32_e32 v67, 0, v67
	v_add_f32_e32 v68, 1.0, v68
	v_log_f32_e32 v68, v68
	v_max_f32_e32 v66, v34, v34
	v_max_f32_e32 v66, 0, v66
	v_add_f32_e32 v67, v67, v68
	v_sub_f32_e32 v50, v50, v67
	v_cndmask_b32_e32 v167, v232, v50, vcc
	v_cndmask_b32_e64 v50, 0, -v67, vcc
	v_exp_f32_e64 v67, -|v34|
	v_exp_f32_e64 v68, -|v51|
	v_add_f32_e32 v67, 1.0, v67
	v_log_f32_e32 v67, v67
	v_add_f32_e32 v68, 1.0, v68
	v_log_f32_e32 v68, v68
	v_add_f32_e32 v66, v66, v67
	v_subrev_u32_e32 v67, 27, v149
	v_cmp_lt_i32_e32 vcc, v67, v130
	v_sub_f32_e32 v34, v34, v66
	s_or_b64 vcc, s[4:5], vcc
	v_max_f32_e32 v67, v51, v51
	v_cndmask_b32_e32 v168, v232, v34, vcc
	v_cndmask_b32_e64 v34, 0, -v66, vcc
	v_subrev_u32_e32 v66, 58, v149
	v_max_f32_e32 v67, 0, v67
	v_add_f32_e32 v67, v67, v68
	v_cmp_lt_i32_e32 vcc, v66, v130
	v_sub_f32_e32 v51, v51, v67
	s_or_b64 vcc, s[4:5], vcc
	v_cndmask_b32_e32 v169, v232, v51, vcc
	v_cndmask_b32_e64 v51, 0, -v67, vcc
	v_exp_f32_e64 v67, -|v35|
	v_exp_f32_e64 v68, -|v52|
	v_max_f32_e32 v66, v35, v35
	v_max_f32_e32 v66, 0, v66
	v_add_f32_e32 v67, 1.0, v67
	v_log_f32_e32 v67, v67
	v_add_f32_e32 v68, 1.0, v68
	v_log_f32_e32 v68, v68
	v_cvt_pk_bf16_f32 v114, v50, v51
	v_add_f32_e32 v66, v66, v67
	v_subrev_u32_e32 v67, 26, v149
	v_cmp_lt_i32_e32 vcc, v67, v130
	v_sub_f32_e32 v35, v35, v66
	s_or_b64 vcc, s[4:5], vcc
	v_max_f32_e32 v67, v52, v52
	v_cndmask_b32_e32 v170, v232, v35, vcc
	v_cndmask_b32_e64 v35, 0, -v66, vcc
	v_subrev_u32_e32 v66, 57, v149
	v_max_f32_e32 v67, 0, v67
	v_add_f32_e32 v67, v67, v68
	v_cmp_lt_i32_e32 vcc, v66, v130
	v_sub_f32_e32 v52, v52, v67
	s_or_b64 vcc, s[4:5], vcc
	v_cndmask_b32_e32 v171, v232, v52, vcc
	v_cndmask_b32_e64 v52, 0, -v67, vcc
	v_exp_f32_e64 v67, -|v36|
	v_exp_f32_e64 v68, -|v53|
	v_max_f32_e32 v66, v36, v36
	v_max_f32_e32 v66, 0, v66
	v_add_f32_e32 v67, 1.0, v67
	v_log_f32_e32 v67, v67
	v_add_f32_e32 v68, 1.0, v68
	v_log_f32_e32 v68, v68
	v_cvt_pk_bf16_f32 v198, v34, v35
	v_add_f32_e32 v66, v66, v67
	v_subrev_u32_e32 v67, 25, v149
	v_cmp_lt_i32_e32 vcc, v67, v130
	v_sub_f32_e32 v36, v36, v66
	s_or_b64 vcc, s[4:5], vcc
	v_max_f32_e32 v67, v53, v53
	v_cndmask_b32_e32 v172, v232, v36, vcc
	v_cndmask_b32_e64 v36, 0, -v66, vcc
	v_subrev_u32_e32 v66, 56, v149
	v_max_f32_e32 v67, 0, v67
	v_add_f32_e32 v67, v67, v68
	v_cmp_lt_i32_e32 vcc, v66, v130
	v_sub_f32_e32 v53, v53, v67
	s_or_b64 vcc, s[4:5], vcc
	v_cndmask_b32_e32 v173, v232, v53, vcc
	v_cndmask_b32_e64 v53, 0, -v67, vcc
	v_exp_f32_e64 v67, -|v37|
	v_exp_f32_e64 v68, -|v54|
	v_max_f32_e32 v66, v37, v37
	v_max_f32_e32 v66, 0, v66
	v_add_f32_e32 v67, 1.0, v67
	v_log_f32_e32 v67, v67
	v_add_f32_e32 v68, 1.0, v68
	v_log_f32_e32 v68, v68
	v_cvt_pk_bf16_f32 v115, v52, v53
	v_add_f32_e32 v66, v66, v67
	v_subrev_u32_e32 v67, 24, v149
	v_cmp_lt_i32_e32 vcc, v67, v130
	v_sub_f32_e32 v37, v37, v66
	s_or_b64 vcc, s[4:5], vcc
	v_max_f32_e32 v67, v54, v54
	v_cndmask_b32_e32 v174, v232, v37, vcc
	v_cndmask_b32_e64 v37, 0, -v66, vcc
	v_subrev_u32_e32 v66, 51, v149
	v_max_f32_e32 v67, 0, v67
	v_add_f32_e32 v67, v67, v68
	v_cmp_lt_i32_e32 vcc, v66, v130
	v_sub_f32_e32 v54, v54, v67
	s_or_b64 vcc, s[4:5], vcc
	v_cndmask_b32_e32 v175, v232, v54, vcc
	v_cndmask_b32_e64 v54, 0, -v67, vcc
	v_exp_f32_e64 v67, -|v38|
	v_exp_f32_e64 v68, -|v55|
	v_max_f32_e32 v66, v38, v38
	v_max_f32_e32 v66, 0, v66
	v_add_f32_e32 v67, 1.0, v67
	v_log_f32_e32 v67, v67
	v_add_f32_e32 v68, 1.0, v68
	v_log_f32_e32 v68, v68
	v_cvt_pk_bf16_f32 v199, v36, v37
	v_add_f32_e32 v66, v66, v67
	v_subrev_u32_e32 v67, 19, v149
	v_cmp_lt_i32_e32 vcc, v67, v130
	v_sub_f32_e32 v38, v38, v66
	s_or_b64 vcc, s[4:5], vcc
	v_max_f32_e32 v67, v55, v55
	v_cndmask_b32_e32 v176, v232, v38, vcc
	v_cndmask_b32_e64 v38, 0, -v66, vcc
	v_subrev_u32_e32 v66, 50, v149
	v_max_f32_e32 v67, 0, v67
	v_add_f32_e32 v67, v67, v68
	v_cmp_lt_i32_e32 vcc, v66, v130
	v_sub_f32_e32 v55, v55, v67
	s_or_b64 vcc, s[4:5], vcc
	v_cndmask_b32_e32 v177, v232, v55, vcc
	v_cndmask_b32_e64 v55, 0, -v67, vcc
	v_exp_f32_e64 v67, -|v39|
	v_exp_f32_e64 v68, -|v56|
	v_max_f32_e32 v66, v39, v39
	v_max_f32_e32 v66, 0, v66
	v_add_f32_e32 v67, 1.0, v67
	v_log_f32_e32 v67, v67
	v_add_f32_e32 v68, 1.0, v68
	v_log_f32_e32 v68, v68
	v_cvt_pk_bf16_f32 v116, v54, v55
	v_add_f32_e32 v66, v66, v67
	v_subrev_u32_e32 v67, 18, v149
	v_cmp_lt_i32_e32 vcc, v67, v130
	v_sub_f32_e32 v39, v39, v66
	s_or_b64 vcc, s[4:5], vcc
	v_max_f32_e32 v67, v56, v56
	v_cndmask_b32_e32 v178, v232, v39, vcc
	v_cndmask_b32_e64 v39, 0, -v66, vcc
	v_subrev_u32_e32 v66, 49, v149
	v_max_f32_e32 v67, 0, v67
	v_add_f32_e32 v67, v67, v68
	v_cmp_lt_i32_e32 vcc, v66, v130
	v_sub_f32_e32 v56, v56, v67
	s_or_b64 vcc, s[4:5], vcc
	v_cndmask_b32_e32 v179, v232, v56, vcc
	v_cndmask_b32_e64 v56, 0, -v67, vcc
	v_exp_f32_e64 v67, -|v40|
	v_exp_f32_e64 v68, -|v57|
	v_max_f32_e32 v66, v40, v40
	v_max_f32_e32 v66, 0, v66
	v_add_f32_e32 v67, 1.0, v67
	v_log_f32_e32 v67, v67
	v_add_f32_e32 v68, 1.0, v68
	v_log_f32_e32 v68, v68
	v_cvt_pk_bf16_f32 v200, v38, v39
	v_add_f32_e32 v66, v66, v67
	v_subrev_u32_e32 v67, 17, v149
	v_cmp_lt_i32_e32 vcc, v67, v130
	v_sub_f32_e32 v40, v40, v66
	s_or_b64 vcc, s[4:5], vcc
	v_max_f32_e32 v67, v57, v57
	v_cndmask_b32_e32 v180, v232, v40, vcc
	v_cndmask_b32_e64 v40, 0, -v66, vcc
	v_subrev_u32_e32 v66, 48, v149
	v_max_f32_e32 v67, 0, v67
	v_add_f32_e32 v67, v67, v68
	v_cmp_lt_i32_e32 vcc, v66, v130
	v_sub_f32_e32 v57, v57, v67
	s_or_b64 vcc, s[4:5], vcc
	v_cndmask_b32_e32 v181, v232, v57, vcc
	v_cndmask_b32_e64 v57, 0, -v67, vcc
	v_exp_f32_e64 v67, -|v41|
	v_exp_f32_e64 v68, -|v58|
	v_max_f32_e32 v66, v41, v41
	v_max_f32_e32 v66, 0, v66
	v_add_f32_e32 v67, 1.0, v67
	v_log_f32_e32 v67, v67
	v_add_f32_e32 v68, 1.0, v68
	v_log_f32_e32 v68, v68
	v_cvt_pk_bf16_f32 v117, v56, v57
	v_add_f32_e32 v66, v66, v67
	v_add_u32_e32 v67, -16, v149
	v_cmp_lt_i32_e32 vcc, v67, v130
	v_sub_f32_e32 v41, v41, v66
	s_or_b64 vcc, s[4:5], vcc
	v_max_f32_e32 v67, v58, v58
	v_cndmask_b32_e32 v182, v232, v41, vcc
	v_cndmask_b32_e64 v41, 0, -v66, vcc
	v_subrev_u32_e32 v66, 43, v149
	v_max_f32_e32 v67, 0, v67
	v_add_f32_e32 v67, v67, v68
	v_cmp_lt_i32_e32 vcc, v66, v130
	v_sub_f32_e32 v58, v58, v67
	s_or_b64 vcc, s[4:5], vcc
	v_cndmask_b32_e32 v183, v232, v58, vcc
	v_cndmask_b32_e64 v58, 0, -v67, vcc
	v_exp_f32_e64 v67, -|v42|
	v_exp_f32_e64 v68, -|v59|
	v_max_f32_e32 v66, v42, v42
	v_max_f32_e32 v66, 0, v66
	v_add_f32_e32 v67, 1.0, v67
	v_log_f32_e32 v67, v67
	v_add_f32_e32 v68, 1.0, v68
	v_log_f32_e32 v68, v68
	v_cvt_pk_bf16_f32 v201, v40, v41
	v_add_f32_e32 v66, v66, v67
	v_add_u32_e32 v67, -11, v149
	v_cmp_lt_i32_e32 vcc, v67, v130
	v_sub_f32_e32 v42, v42, v66
	s_or_b64 vcc, s[4:5], vcc
	v_max_f32_e32 v67, v59, v59
	v_cndmask_b32_e32 v184, v232, v42, vcc
	v_cndmask_b32_e64 v42, 0, -v66, vcc
	v_subrev_u32_e32 v66, 42, v149
	v_max_f32_e32 v67, 0, v67
	v_add_f32_e32 v67, v67, v68
	v_cmp_lt_i32_e32 vcc, v66, v130
	v_sub_f32_e32 v59, v59, v67
	s_or_b64 vcc, s[4:5], vcc
	v_cndmask_b32_e32 v185, v232, v59, vcc
	v_cndmask_b32_e64 v59, 0, -v67, vcc
	v_exp_f32_e64 v67, -|v43|
	v_exp_f32_e64 v68, -|v60|
	v_max_f32_e32 v66, v43, v43
	v_max_f32_e32 v66, 0, v66
	v_add_f32_e32 v67, 1.0, v67
	v_log_f32_e32 v67, v67
	v_add_f32_e32 v68, 1.0, v68
	v_log_f32_e32 v68, v68
	v_cvt_pk_bf16_f32 v122, v58, v59
	v_add_f32_e32 v66, v66, v67
	v_add_u32_e32 v67, -10, v149
	v_cmp_lt_i32_e32 vcc, v67, v130
	v_sub_f32_e32 v43, v43, v66
	s_or_b64 vcc, s[4:5], vcc
	v_max_f32_e32 v67, v60, v60
	v_cndmask_b32_e32 v186, v232, v43, vcc
	v_cndmask_b32_e64 v43, 0, -v66, vcc
	v_subrev_u32_e32 v66, 41, v149
	v_max_f32_e32 v67, 0, v67
	v_add_f32_e32 v67, v67, v68
	v_cmp_lt_i32_e32 vcc, v66, v130
	v_sub_f32_e32 v60, v60, v67
	s_or_b64 vcc, s[4:5], vcc
	v_cndmask_b32_e32 v187, v232, v60, vcc
	v_cndmask_b32_e64 v60, 0, -v67, vcc
	v_exp_f32_e64 v67, -|v44|
	v_exp_f32_e64 v68, -|v61|
	v_max_f32_e32 v66, v44, v44
	v_max_f32_e32 v66, 0, v66
	v_add_f32_e32 v67, 1.0, v67
	v_log_f32_e32 v67, v67
	v_add_f32_e32 v68, 1.0, v68
	v_log_f32_e32 v68, v68
	v_add_f32_e32 v66, v66, v67
	v_add_u32_e32 v67, -9, v149
	v_cmp_lt_i32_e32 vcc, v67, v130
	v_sub_f32_e32 v44, v44, v66
	s_or_b64 vcc, s[4:5], vcc
	v_max_f32_e32 v67, v61, v61
	v_cndmask_b32_e32 v188, v232, v44, vcc
	v_cndmask_b32_e64 v44, 0, -v66, vcc
	v_subrev_u32_e32 v66, 40, v149
	v_max_f32_e32 v67, 0, v67
	v_add_f32_e32 v67, v67, v68
	v_cmp_lt_i32_e32 vcc, v66, v130
	v_sub_f32_e32 v61, v61, v67
	s_or_b64 vcc, s[4:5], vcc
	v_cndmask_b32_e32 v189, v232, v61, vcc
	v_cndmask_b32_e64 v61, 0, -v67, vcc
	v_exp_f32_e64 v67, -|v45|
	v_exp_f32_e64 v68, -|v62|
	v_max_f32_e32 v66, v45, v45
	v_max_f32_e32 v66, 0, v66
	v_add_f32_e32 v67, 1.0, v67
	v_log_f32_e32 v67, v67
	v_add_f32_e32 v68, 1.0, v68
	v_log_f32_e32 v68, v68
	v_cvt_pk_bf16_f32 v123, v60, v61
	v_add_f32_e32 v66, v66, v67
	v_add_u32_e32 v67, -8, v149
	v_cmp_lt_i32_e32 vcc, v67, v130
	v_sub_f32_e32 v45, v45, v66
	s_or_b64 vcc, s[4:5], vcc
	v_max_f32_e32 v67, v62, v62
	v_cndmask_b32_e32 v190, v232, v45, vcc
	v_cndmask_b32_e64 v45, 0, -v66, vcc
	v_subrev_u32_e32 v66, 35, v149
	v_max_f32_e32 v67, 0, v67
	v_add_f32_e32 v67, v67, v68
	v_cmp_lt_i32_e32 vcc, v66, v130
	v_sub_f32_e32 v62, v62, v67
	s_or_b64 vcc, s[4:5], vcc
	v_cndmask_b32_e32 v191, v232, v62, vcc
	v_cndmask_b32_e64 v62, 0, -v67, vcc
	v_exp_f32_e64 v67, -|v46|
	v_exp_f32_e64 v68, -|v63|
	v_max_f32_e32 v66, v46, v46
	v_max_f32_e32 v66, 0, v66
	v_add_f32_e32 v67, 1.0, v67
	v_log_f32_e32 v67, v67
	v_add_f32_e32 v68, 1.0, v68
	v_log_f32_e32 v68, v68
	v_add_f32_e32 v66, v66, v67
	v_add_u32_e32 v67, -3, v149
	v_cmp_lt_i32_e32 vcc, v67, v130
	v_sub_f32_e32 v46, v46, v66
	s_or_b64 vcc, s[4:5], vcc
	v_max_f32_e32 v67, v63, v63
	v_cndmask_b32_e32 v192, v232, v46, vcc
	v_cndmask_b32_e64 v46, 0, -v66, vcc
	v_subrev_u32_e32 v66, 34, v149
	v_max_f32_e32 v67, 0, v67
	v_add_f32_e32 v67, v67, v68
	v_cmp_lt_i32_e32 vcc, v66, v130
	v_sub_f32_e32 v63, v63, v67
	s_or_b64 vcc, s[4:5], vcc
	v_cndmask_b32_e32 v193, v232, v63, vcc
	v_cndmask_b32_e64 v63, 0, -v67, vcc
	v_exp_f32_e64 v67, -|v47|
	v_exp_f32_e64 v68, -|v64|
	v_max_f32_e32 v66, v47, v47
	v_max_f32_e32 v66, 0, v66
	v_add_f32_e32 v67, 1.0, v67
	v_log_f32_e32 v67, v67
	v_add_f32_e32 v68, 1.0, v68
	v_log_f32_e32 v68, v68
	v_cvt_pk_bf16_f32 v124, v62, v63
	v_add_f32_e32 v66, v66, v67
	v_add_u32_e32 v67, -2, v149
	v_cmp_lt_i32_e32 vcc, v67, v130
	v_sub_f32_e32 v47, v47, v66
	s_or_b64 vcc, s[4:5], vcc
	v_max_f32_e32 v67, v64, v64
	v_cndmask_b32_e32 v194, v232, v47, vcc
	v_cndmask_b32_e64 v47, 0, -v66, vcc
	v_subrev_u32_e32 v66, 33, v149
	v_max_f32_e32 v67, 0, v67
	v_add_f32_e32 v67, v67, v68
	v_cmp_lt_i32_e32 vcc, v66, v130
	v_sub_f32_e32 v64, v64, v67
	s_or_b64 vcc, s[4:5], vcc
	v_cndmask_b32_e32 v196, v232, v64, vcc
	v_cndmask_b32_e64 v64, 0, -v67, vcc
	v_exp_f32_e64 v67, -|v48|
	v_exp_f32_e64 v68, -|v65|
	v_max_f32_e32 v66, v48, v48
	v_max_f32_e32 v66, 0, v66
	v_add_f32_e32 v67, 1.0, v67
	v_log_f32_e32 v67, v67
	v_add_f32_e32 v68, 1.0, v68
	v_log_f32_e32 v68, v68
	v_add_f32_e32 v66, v66, v67
	v_add_u32_e32 v67, -1, v149
	v_cmp_lt_i32_e32 vcc, v67, v130
	v_sub_f32_e32 v48, v48, v66
	s_or_b64 vcc, s[4:5], vcc
	v_max_f32_e32 v67, v65, v65
	v_cndmask_b32_e32 v197, v232, v48, vcc
	v_cndmask_b32_e64 v48, 0, -v66, vcc
	v_subrev_u32_e32 v66, 32, v149
	v_max_f32_e32 v67, 0, v67
	v_add_f32_e32 v67, v67, v68
	v_cmp_lt_i32_e32 vcc, v66, v130
	v_sub_f32_e32 v65, v65, v67
	s_or_b64 vcc, s[4:5], vcc
	v_cndmask_b32_e32 v202, v232, v65, vcc
	v_cndmask_b32_e64 v65, 0, -v67, vcc
	v_exp_f32_e64 v67, -|v49|
	v_max_f32_e32 v66, v49, v49
	v_max_f32_e32 v66, 0, v66
	v_cmp_lt_i32_e32 vcc, v149, v130
	v_add_f32_e32 v67, 1.0, v67
	v_log_f32_e32 v67, v67
	s_or_b64 vcc, s[4:5], vcc
	v_cvt_pk_bf16_f32 v68, v46, v47
	v_cvt_pk_bf16_f32 v125, v64, v65
	v_add_f32_e32 v66, v66, v67
	v_sub_f32_e32 v49, v49, v66
	v_cndmask_b32_e32 v203, v232, v49, vcc
	v_cndmask_b32_e64 v49, 0, -v66, vcc
	v_cvt_pk_bf16_f32 v66, v42, v43
	v_cvt_pk_bf16_f32 v67, v44, v45
	v_cvt_pk_bf16_f32 v69, v48, v49
	s_branch .Lsb_join
.Lsb_fast:
	s_nop 4
	v_exp_f32_e64 v204, -|v50|
	v_exp_f32_e64 v205, -|v51|
	v_exp_f32_e64 v206, -|v52|
	v_exp_f32_e64 v207, -|v53|
	v_add_f32_e32 v204, 1.0, v204
	v_add_f32_e32 v205, 1.0, v205
	v_add_f32_e32 v206, 1.0, v206
	v_add_f32_e32 v207, 1.0, v207
	v_log_f32_e32 v204, v204
	v_log_f32_e32 v205, v205
	v_log_f32_e32 v206, v206
	v_log_f32_e32 v207, v207
	v_max_f32_e32 v208, 0, v50
	v_max_f32_e32 v209, 0, v51
	v_max_f32_e32 v210, 0, v52
	v_max_f32_e32 v211, 0, v53
	v_add_f32_e32 v204, v208, v204
	v_add_f32_e32 v205, v209, v205
	v_add_f32_e32 v206, v210, v206
	v_add_f32_e32 v207, v211, v207
	v_sub_f32_e32 v167, v50, v204
	v_sub_f32_e32 v169, v51, v205
	v_sub_f32_e32 v171, v52, v206
	v_sub_f32_e32 v173, v53, v207
	v_cvt_pk_bf16_f32 v114, -v204, -v205
	v_cvt_pk_bf16_f32 v115, -v206, -v207
	v_exp_f32_e64 v204, -|v54|
	v_exp_f32_e64 v205, -|v55|
	v_exp_f32_e64 v206, -|v56|
	v_exp_f32_e64 v207, -|v57|
	v_add_f32_e32 v204, 1.0, v204
	v_add_f32_e32 v205, 1.0, v205
	v_add_f32_e32 v206, 1.0, v206
	v_add_f32_e32 v207, 1.0, v207
	v_log_f32_e32 v204, v204
	v_log_f32_e32 v205, v205
	v_log_f32_e32 v206, v206
	v_log_f32_e32 v207, v207
	v_max_f32_e32 v208, 0, v54
	v_max_f32_e32 v209, 0, v55
	v_max_f32_e32 v210, 0, v56
	v_max_f32_e32 v211, 0, v57
	v_add_f32_e32 v204, v208, v204
	v_add_f32_e32 v205, v209, v205
	v_add_f32_e32 v206, v210, v206
	v_add_f32_e32 v207, v211, v207
	v_sub_f32_e32 v175, v54, v204
	v_sub_f32_e32 v177, v55, v205
	v_sub_f32_e32 v179, v56, v206
	v_sub_f32_e32 v181, v57, v207
	v_cvt_pk_bf16_f32 v116, -v204, -v205
	v_cvt_pk_bf16_f32 v117, -v206, -v207
	v_exp_f32_e64 v204, -|v58|
	v_exp_f32_e64 v205, -|v59|
	v_exp_f32_e64 v206, -|v60|
	v_exp_f32_e64 v207, -|v61|
	v_add_f32_e32 v204, 1.0, v204
	v_add_f32_e32 v205, 1.0, v205
	v_add_f32_e32 v206, 1.0, v206
	v_add_f32_e32 v207, 1.0, v207
	v_log_f32_e32 v204, v204
	v_log_f32_e32 v205, v205
	v_log_f32_e32 v206, v206
	v_log_f32_e32 v207, v207
	v_max_f32_e32 v208, 0, v58
	v_max_f32_e32 v209, 0, v59
	v_max_f32_e32 v210, 0, v60
	v_max_f32_e32 v211, 0, v61
	v_add_f32_e32 v204, v208, v204
	v_add_f32_e32 v205, v209, v205
	v_add_f32_e32 v206, v210, v206
	v_add_f32_e32 v207, v211, v207
	v_sub_f32_e32 v183, v58, v204
	v_sub_f32_e32 v185, v59, v205
	v_sub_f32_e32 v187, v60, v206
	v_sub_f32_e32 v189, v61, v207
	v_cvt_pk_bf16_f32 v122, -v204, -v205
	v_cvt_pk_bf16_f32 v123, -v206, -v207
	v_exp_f32_e64 v204, -|v62|
	v_exp_f32_e64 v205, -|v63|
	v_exp_f32_e64 v206, -|v64|
	v_exp_f32_e64 v207, -|v65|
	v_add_f32_e32 v204, 1.0, v204
	v_add_f32_e32 v205, 1.0, v205
	v_add_f32_e32 v206, 1.0, v206
	v_add_f32_e32 v207, 1.0, v207
	v_log_f32_e32 v204, v204
	v_log_f32_e32 v205, v205
	v_log_f32_e32 v206, v206
	v_log_f32_e32 v207, v207
	v_max_f32_e32 v208, 0, v62
	v_max_f32_e32 v209, 0, v63
	v_max_f32_e32 v210, 0, v64
	v_max_f32_e32 v211, 0, v65
	v_add_f32_e32 v204, v208, v204
	v_add_f32_e32 v205, v209, v205
	v_add_f32_e32 v206, v210, v206
	v_add_f32_e32 v207, v211, v207
	v_sub_f32_e32 v191, v62, v204
	v_sub_f32_e32 v193, v63, v205
	v_sub_f32_e32 v196, v64, v206
	v_sub_f32_e32 v202, v65, v207
	v_cvt_pk_bf16_f32 v124, -v204, -v205
	v_cvt_pk_bf16_f32 v125, -v206, -v207
	v_exp_f32_e64 v204, -|v34|
	v_exp_f32_e64 v205, -|v35|
	v_exp_f32_e64 v206, -|v36|
	v_exp_f32_e64 v207, -|v37|
	v_add_f32_e32 v204, 1.0, v204
	v_add_f32_e32 v205, 1.0, v205
	v_add_f32_e32 v206, 1.0, v206
	v_add_f32_e32 v207, 1.0, v207
	v_log_f32_e32 v204, v204
	v_log_f32_e32 v205, v205
	v_log_f32_e32 v206, v206
	v_log_f32_e32 v207, v207
	v_max_f32_e32 v208, 0, v34
	v_max_f32_e32 v209, 0, v35
	v_max_f32_e32 v210, 0, v36
	v_max_f32_e32 v211, 0, v37
	v_add_f32_e32 v204, v208, v204
	v_add_f32_e32 v205, v209, v205
	v_add_f32_e32 v206, v210, v206
	v_add_f32_e32 v207, v211, v207
	v_sub_f32_e32 v168, v34, v204
	v_sub_f32_e32 v170, v35, v205
	v_sub_f32_e32 v172, v36, v206
	v_sub_f32_e32 v174, v37, v207
	v_cvt_pk_bf16_f32 v198, -v204, -v205
	v_cvt_pk_bf16_f32 v199, -v206, -v207
	v_exp_f32_e64 v204, -|v38|
	v_exp_f32_e64 v205, -|v39|
	v_exp_f32_e64 v206, -|v40|
	v_exp_f32_e64 v207, -|v41|
	v_add_f32_e32 v204, 1.0, v204
	v_add_f32_e32 v205, 1.0, v205
	v_add_f32_e32 v206, 1.0, v206
	v_add_f32_e32 v207, 1.0, v207
	v_log_f32_e32 v204, v204
	v_log_f32_e32 v205, v205
	v_log_f32_e32 v206, v206
	v_log_f32_e32 v207, v207
	v_max_f32_e32 v208, 0, v38
	v_max_f32_e32 v209, 0, v39
	v_max_f32_e32 v210, 0, v40
	v_max_f32_e32 v211, 0, v41
	v_add_f32_e32 v204, v208, v204
	v_add_f32_e32 v205, v209, v205
	v_add_f32_e32 v206, v210, v206
	v_add_f32_e32 v207, v211, v207
	v_sub_f32_e32 v176, v38, v204
	v_sub_f32_e32 v178, v39, v205
	v_sub_f32_e32 v180, v40, v206
	v_sub_f32_e32 v182, v41, v207
	v_cvt_pk_bf16_f32 v200, -v204, -v205
	v_cvt_pk_bf16_f32 v201, -v206, -v207
	v_exp_f32_e64 v204, -|v42|
	v_exp_f32_e64 v205, -|v43|
	v_exp_f32_e64 v206, -|v44|
	v_exp_f32_e64 v207, -|v45|
	v_add_f32_e32 v204, 1.0, v204
	v_add_f32_e32 v205, 1.0, v205
	v_add_f32_e32 v206, 1.0, v206
	v_add_f32_e32 v207, 1.0, v207
	v_log_f32_e32 v204, v204
	v_log_f32_e32 v205, v205
	v_log_f32_e32 v206, v206
	v_log_f32_e32 v207, v207
	v_max_f32_e32 v208, 0, v42
	v_max_f32_e32 v209, 0, v43
	v_max_f32_e32 v210, 0, v44
	v_max_f32_e32 v211, 0, v45
	v_add_f32_e32 v204, v208, v204
	v_add_f32_e32 v205, v209, v205
	v_add_f32_e32 v206, v210, v206
	v_add_f32_e32 v207, v211, v207
	v_sub_f32_e32 v184, v42, v204
	v_sub_f32_e32 v186, v43, v205
	v_sub_f32_e32 v188, v44, v206
	v_sub_f32_e32 v190, v45, v207
	v_cvt_pk_bf16_f32 v66, -v204, -v205
	v_cvt_pk_bf16_f32 v67, -v206, -v207
	v_exp_f32_e64 v204, -|v46|
	v_exp_f32_e64 v205, -|v47|
	v_exp_f32_e64 v206, -|v48|
	v_exp_f32_e64 v207, -|v49|
	v_add_f32_e32 v204, 1.0, v204
	v_add_f32_e32 v205, 1.0, v205
	v_add_f32_e32 v206, 1.0, v206
	v_add_f32_e32 v207, 1.0, v207
	v_log_f32_e32 v204, v204
	v_log_f32_e32 v205, v205
	v_log_f32_e32 v206, v206
	v_log_f32_e32 v207, v207
	v_max_f32_e32 v208, 0, v46
	v_max_f32_e32 v209, 0, v47
	v_max_f32_e32 v210, 0, v48
	v_max_f32_e32 v211, 0, v49
	v_add_f32_e32 v204, v208, v204
	v_add_f32_e32 v205, v209, v205
	v_add_f32_e32 v206, v210, v206
	v_add_f32_e32 v207, v211, v207
	v_sub_f32_e32 v192, v46, v204
	v_sub_f32_e32 v194, v47, v205
	v_sub_f32_e32 v197, v48, v206
	v_sub_f32_e32 v203, v49, v207
	v_cvt_pk_bf16_f32 v68, -v204, -v205
	v_cvt_pk_bf16_f32 v69, -v206, -v207
.Lsb_join:
	s_mov_b32 s4, s16
	v_writelane_b32 v252, s4, 30
	v_mfma_f32_32x32x16_bf16 v[34:49], v[118:121], v[66:69], 0
	s_nop 0
	v_writelane_b32 v252, s5, 31
	v_writelane_b32 v252, s6, 32
	v_writelane_b32 v252, s7, 33
	s_mov_b32 s4, 0xc3200000
	v_mfma_f32_32x32x16_bf16 v[34:49], v[118:121], v[198:201], v[34:49]
	v_mfma_f32_32x32x16_bf16 v[50:65], v[110:113], v[122:125], v[34:49]
	v_mfma_f32_32x32x16_bf16 v[50:65], v[106:109], v[114:117], v[50:65]
	v_mfma_f32_32x32x16_bf16 v[34:49], v[118:121], v[122:125], v[34:49]
	s_nop 10
	v_add_f32_e32 v50, v50, v167
	v_add_f32_e32 v51, v51, v169
	v_add_f32_e32 v52, v52, v171
	v_add_f32_e32 v53, v53, v173
	v_add_f32_e32 v50, v151, v50
	v_add_f32_e32 v51, v151, v51
	v_add_f32_e32 v52, v151, v52
	v_add_f32_e32 v53, v151, v53
	v_exp_f32_e32 v50, v50
	v_exp_f32_e32 v51, v51
	v_exp_f32_e32 v52, v52
	v_exp_f32_e32 v53, v53
	v_mfma_f32_32x32x16_bf16 v[34:49], v[118:121], v[114:117], v[34:49]
	v_add_f32_e32 v54, v54, v175
	v_add_f32_e32 v55, v55, v177
	v_add_f32_e32 v56, v56, v179
	v_add_f32_e32 v57, v57, v181
	v_add_f32_e32 v54, v151, v54
	s_nop 6
	v_cvt_pk_bf16_f32 v46, v50, v51
	v_cvt_pk_bf16_f32 v47, v52, v53
	v_add_u32_e32 v50, s15, v166
	v_add_u32_e32 v52, s15, v165
	ds_read_b64_tr_b16 v[50:51], v50
	ds_read_b64_tr_b16 v[52:53], v52
	v_add_f32_e32 v55, v151, v55
	v_add_f32_e32 v56, v151, v56
	v_add_f32_e32 v57, v151, v57
	v_exp_f32_e32 v54, v54
	v_exp_f32_e32 v55, v55
	v_exp_f32_e32 v56, v56
	v_exp_f32_e32 v57, v57
	v_mfma_f32_32x32x16_bf16 v[66:81], v[110:113], v[66:69], 0
	v_cvt_pk_bf16_f32 v48, v54, v55
	v_add_f32_e32 v58, v58, v183
	v_cvt_pk_bf16_f32 v49, v56, v57
	v_add_f32_e32 v59, v59, v185
	v_add_f32_e32 v60, v60, v187
	v_add_f32_e32 v61, v61, v189
	v_add_f32_e32 v62, v62, v191
	s_waitcnt lgkmcnt(0)
	v_mfma_f32_32x32x16_bf16 v[18:33], v[50:53], v[46:49], v[18:33]
	v_add_u32_e32 v50, s15, v164
	v_add_u32_e32 v52, s15, v163
	ds_read_b64_tr_b16 v[50:51], v50
	ds_read_b64_tr_b16 v[52:53], v52
	v_add_f32_e32 v63, v63, v193
	v_add_f32_e32 v64, v64, v196
	v_add_f32_e32 v65, v65, v202
	v_add_f32_e32 v58, v151, v58
	v_add_f32_e32 v59, v151, v59
	v_add_f32_e32 v60, v151, v60
	v_add_f32_e32 v61, v151, v61
	v_add_f32_e32 v62, v151, v62
	v_add_f32_e32 v63, v151, v63
	v_add_f32_e32 v64, v151, v64
	v_add_f32_e32 v65, v151, v65
	v_mfma_f32_32x32x16_bf16 v[66:81], v[106:109], v[198:201], v[66:81]
	v_exp_f32_e32 v58, v58
	v_exp_f32_e32 v59, v59
	v_exp_f32_e32 v60, v60
	v_exp_f32_e32 v61, v61
	v_exp_f32_e32 v62, v62
	v_exp_f32_e32 v63, v63
	v_exp_f32_e32 v64, v64
	v_exp_f32_e32 v65, v65
	v_cvt_pk_bf16_f32 v42, v58, v59
	v_cvt_pk_bf16_f32 v43, v60, v61
	v_cvt_pk_bf16_f32 v44, v62, v63
	v_cvt_pk_bf16_f32 v45, v64, v65
	v_add_f32_e32 v66, v66, v168
	v_add_f32_e32 v67, v67, v170
	s_waitcnt lgkmcnt(0)
	v_mfma_f32_32x32x16_bf16 v[18:33], v[50:53], v[42:45], v[18:33]
	v_add_u32_e32 v50, s15, v162
	v_add_u32_e32 v52, s15, v161
	ds_read_b64_tr_b16 v[50:51], v50
	ds_read_b64_tr_b16 v[52:53], v52
	v_add_f32_e32 v68, v68, v172
	v_add_f32_e32 v69, v69, v174
	v_add_f32_e32 v70, v70, v176
	v_add_f32_e32 v71, v71, v178
	v_add_f32_e32 v72, v72, v180
	v_add_f32_e32 v73, v73, v182
	v_add_f32_e32 v66, v151, v66
	v_add_f32_e32 v67, v151, v67
	v_add_f32_e32 v68, v151, v68
	v_add_f32_e32 v69, v151, v69
	v_add_f32_e32 v70, v151, v70
	v_add_f32_e32 v71, v151, v71
	v_add_f32_e32 v72, v151, v72
	v_add_f32_e32 v73, v151, v73
	v_exp_f32_e32 v66, v66
	v_exp_f32_e32 v67, v67
	v_exp_f32_e32 v68, v68
	v_exp_f32_e32 v69, v69
	v_exp_f32_e32 v70, v70
	v_exp_f32_e32 v71, v71
	v_exp_f32_e32 v72, v72
	v_exp_f32_e32 v73, v73
	v_cvt_pk_bf16_f32 v38, v66, v67
	v_cvt_pk_bf16_f32 v39, v68, v69
	v_cvt_pk_bf16_f32 v40, v70, v71
	v_cvt_pk_bf16_f32 v41, v72, v73
	v_add_f32_e32 v74, v74, v184
	v_add_f32_e32 v75, v75, v186
	s_waitcnt lgkmcnt(0)
	v_mfma_f32_32x32x16_bf16 v[18:33], v[50:53], v[38:41], v[18:33]
	v_add_u32_e32 v50, s15, v160
	v_add_u32_e32 v52, s15, v159
	ds_read_b64_tr_b16 v[50:51], v50
	ds_read_b64_tr_b16 v[52:53], v52
	v_add_f32_e32 v76, v76, v188
	v_add_f32_e32 v77, v77, v190
	v_add_f32_e32 v78, v78, v192
	v_add_f32_e32 v79, v79, v194
	v_add_f32_e32 v80, v80, v197
	v_add_f32_e32 v81, v81, v203
	v_add_f32_e32 v74, v151, v74
	v_add_f32_e32 v75, v151, v75
	v_add_f32_e32 v76, v151, v76
	v_add_f32_e32 v77, v151, v77
	v_add_f32_e32 v78, v151, v78
	v_add_f32_e32 v79, v151, v79
	v_add_f32_e32 v80, v151, v80
	v_add_f32_e32 v81, v151, v81
	v_exp_f32_e32 v74, v74
	v_exp_f32_e32 v75, v75
	v_exp_f32_e32 v76, v76
	v_exp_f32_e32 v77, v77
	v_exp_f32_e32 v78, v78
	v_exp_f32_e32 v79, v79
	v_exp_f32_e32 v80, v80
	v_exp_f32_e32 v81, v81
	v_add_f32_e32 v151, v151, v34
	v_cvt_pk_bf16_f32 v34, v74, v75
	v_cvt_pk_bf16_f32 v35, v76, v77
	v_cvt_pk_bf16_f32 v36, v78, v79
	v_cvt_pk_bf16_f32 v37, v80, v81
	v_cmp_gt_f32_e32 vcc, s4, v151
	s_cmp_eq_u64 vcc, exec
	s_waitcnt lgkmcnt(0)
	v_mfma_f32_32x32x16_bf16 v[18:33], v[50:53], v[34:37], v[18:33]
	v_add_u32_e32 v50, s15, v158
	v_add_u32_e32 v52, s15, v157
	ds_read_b64_tr_b16 v[50:51], v50
	ds_read_b64_tr_b16 v[52:53], v52
	s_cselect_b64 s[4:5], -1, 0
	s_and_b64 s[16:17], s[0:1], s[4:5]
	s_waitcnt lgkmcnt(0)
	v_mfma_f32_32x32x16_bf16 v[2:17], v[50:53], v[46:49], v[2:17]
	v_add_u32_e32 v46, s15, v156
	v_add_u32_e32 v48, s15, v155
	ds_read_b64_tr_b16 v[46:47], v46
	ds_read_b64_tr_b16 v[48:49], v48
	s_waitcnt lgkmcnt(0)
	v_mfma_f32_32x32x16_bf16 v[2:17], v[46:49], v[42:45], v[2:17]
	v_add_u32_e32 v42, s15, v154
	v_add_u32_e32 v44, s15, v153
	ds_read_b64_tr_b16 v[42:43], v42
	ds_read_b64_tr_b16 v[44:45], v44
	s_waitcnt lgkmcnt(0)
	v_mfma_f32_32x32x16_bf16 v[2:17], v[42:45], v[38:41], v[2:17]
	v_add_u32_e32 v38, s15, v152
	ds_read_b64_tr_b16 v[38:39], v38
	ds_read_b64_tr_b16 v[40:41], v1
	s_waitcnt lgkmcnt(0)
	v_mfma_f32_32x32x16_bf16 v[2:17], v[38:41], v[34:37], v[2:17]
	s_and_saveexec_b64 s[4:5], s[16:17]
	v_mov_b32_e32 v1, s8
	ds_write_b32 v1, v223
	s_or_b64 exec, exec, s[4:5]

; #define LOAD_TILE(KR, VR, tl) do { KR = *(const GAS u32x4*)(kg + (size_t)(tl) * 64 * LDH); VR = *(const GAS u32x4*)(vg + (size_t)(tl) * 64 * LDH); } while (0)
; template <int MODE> ...
;     ...
;     for (int it = 0; it < ntiles && !stop; it += 2) {
;         LOAD_TILE(kreg, vreg, TILE_OF(min(it + 2, ntiles - 1)));
;         COMPUTE_TILE(TILE_OF(it), 0);
.LBB0_824:
	s_add_i32 s12, s13, 2
	s_min_i32 s4, s12, s10
	v_mad_u64_u32 v[34:35], s[4:5], s4, v231, v[98:99]
	global_load_dwordx4 v[90:93], v[34:35], off offset:768
	global_load_dwordx4 v[94:97], v[34:35], off offset:1536
	s_cmp_gt_i32 s13, s9
	s_cbranch_scc1 .LBB0_832
	ds_read_b128 v[34:37], v110
	ds_read_b128 v[38:41], v110 offset:32
	ds_read_b128 v[42:45], v110 offset:64
	ds_read_b128 v[46:49], v110 offset:96
	ds_read_b128 v[116:119], v113
	ds_read_b128 v[120:123], v113 offset:32
	ds_read_b128 v[124:127], v113 offset:64
	ds_read_b128 v[182:185], v113 offset:96
	ds_read_b128 v[50:53], v110 offset:128
	ds_read_b128 v[54:57], v110 offset:160
	ds_read_b128 v[58:61], v110 offset:192
	ds_read_b128 v[62:65], v110 offset:224
	ds_read_b128 v[186:189], v113 offset:4608
	ds_read_b128 v[190:193], v113 offset:4640
	ds_read_b128 v[242:245], v113 offset:4672
	ds_read_b128 v[246:249], v113 offset:4704
	v_sub_f32_e32 v1, v105, v112
	s_waitcnt lgkmcnt(12)
	v_sub_f32_e32 v34, v1, v34
	v_sub_f32_e32 v35, v1, v35
	v_sub_f32_e32 v36, v1, v36
	v_sub_f32_e32 v37, v1, v37
	v_sub_f32_e32 v38, v1, v38
	v_sub_f32_e32 v39, v1, v39
	v_sub_f32_e32 v40, v1, v40
	v_sub_f32_e32 v41, v1, v41
	v_sub_f32_e32 v42, v1, v42
	v_sub_f32_e32 v43, v1, v43
	v_sub_f32_e32 v44, v1, v44
	v_sub_f32_e32 v45, v1, v45
	v_sub_f32_e32 v46, v1, v46
	v_sub_f32_e32 v47, v1, v47
	v_sub_f32_e32 v48, v1, v48
	v_sub_f32_e32 v49, v1, v49
	s_waitcnt vmcnt(4) lgkmcnt(4)
	v_mfma_f32_32x32x16_bf16 v[34:49], v[116:119], v[66:69], v[34:49]
	v_sub_f32_e32 v50, v1, v50
	v_sub_f32_e32 v51, v1, v51
	v_sub_f32_e32 v52, v1, v52
	v_sub_f32_e32 v53, v1, v53
	s_waitcnt lgkmcnt(4)
	v_mfma_f32_32x32x16_bf16 v[34:49], v[120:123], v[70:73], v[34:49]
	v_sub_f32_e32 v54, v1, v54
	v_sub_f32_e32 v55, v1, v55
	v_sub_f32_e32 v56, v1, v56
	v_sub_f32_e32 v57, v1, v57
	s_waitcnt lgkmcnt(4)
	v_mfma_f32_32x32x16_bf16 v[34:49], v[124:127], v[74:77], v[34:49]
	v_sub_f32_e32 v58, v1, v58
	v_sub_f32_e32 v59, v1, v59
	v_sub_f32_e32 v60, v1, v60
	v_sub_f32_e32 v61, v1, v61
	s_waitcnt lgkmcnt(0)
	v_mfma_f32_32x32x16_bf16 v[34:49], v[182:185], v[78:81], v[34:49]
	v_sub_f32_e32 v62, v1, v62
	v_sub_f32_e32 v63, v1, v63
	v_sub_f32_e32 v64, v1, v64
	v_sub_f32_e32 v65, v1, v65
	s_nop 1
	v_mfma_f32_32x32x16_bf16 v[50:65], v[186:189], v[66:69], v[50:65]
	ds_read_b64_tr_b16 v[198:199], v108 offset:9216
	ds_read_b64_tr_b16 v[200:201], v108 offset:10368
	ds_read_b64_tr_b16 v[202:203], v108 offset:11520
	ds_read_b64_tr_b16 v[204:205], v108 offset:12672
	v_mfma_f32_32x32x16_bf16 v[50:65], v[190:193], v[70:73], v[50:65]
	ds_read_b64_tr_b16 v[206:207], v108 offset:13824
	ds_read_b64_tr_b16 v[208:209], v108 offset:14976
	ds_read_b64_tr_b16 v[210:211], v108 offset:16128
	ds_read_b64_tr_b16 v[212:213], v108 offset:17280
	v_mfma_f32_32x32x16_bf16 v[50:65], v[242:245], v[74:77], v[50:65]
	ds_read_b64_tr_b16 v[214:215], v108 offset:9280
	ds_read_b64_tr_b16 v[216:217], v108 offset:10432
	ds_read_b64_tr_b16 v[218:219], v108 offset:11584
	ds_read_b64_tr_b16 v[220:221], v108 offset:12736
	v_mfma_f32_32x32x16_bf16 v[50:65], v[246:249], v[78:81], v[50:65]
	ds_read_b64_tr_b16 v[234:235], v108 offset:13888
	ds_read_b64_tr_b16 v[236:237], v108 offset:15040
	ds_read_b64_tr_b16 v[238:239], v108 offset:16192
	ds_read_b64_tr_b16 v[240:241], v108 offset:17344
	s_nop 1
	s_cmp_lg_u32 s9, s13
	s_cbranch_scc1 .LBB0_827
	v_add_u32_e32 v104, 0xffffffa5, v111
	v_add_u32_e32 v1, 0xffffff85, v111
	v_cmp_le_i32_e32 vcc, v104, v102
	s_nop 7
	v_cndmask_b32_e32 v50, v232, v50, vcc
	v_cmp_lt_i32_e32 vcc, v1, v102
	s_nop 1
	v_cndmask_b32_e32 v35, v232, v35, vcc
	v_cmp_le_i32_e32 vcc, v1, v102
	v_add_u32_e32 v1, 0xffffffa6, v111
	s_nop 0
	v_cndmask_b32_e32 v34, v232, v34, vcc
	v_cmp_le_i32_e32 vcc, v1, v102
	v_add_u32_e32 v1, 0xffffff87, v111
	s_nop 0
	v_cndmask_b32_e32 v51, v232, v51, vcc
	v_cmp_le_i32_e32 vcc, v1, v102
	v_add_u32_e32 v1, 0xffffffa7, v111
	s_nop 0
	v_cndmask_b32_e32 v36, v232, v36, vcc
	v_cmp_le_i32_e32 vcc, v1, v102
	v_add_u32_e32 v1, 0xffffff88, v111
	s_nop 0
	v_cndmask_b32_e32 v52, v232, v52, vcc
	v_cmp_le_i32_e32 vcc, v1, v102
	v_add_u32_e32 v1, 0xffffffa8, v111
	s_nop 0
	v_cndmask_b32_e32 v37, v232, v37, vcc
	v_cmp_le_i32_e32 vcc, v1, v102
	v_add_u32_e32 v1, 0xffffff8d, v111
	s_nop 0
	v_cndmask_b32_e32 v53, v232, v53, vcc
	v_cmp_le_i32_e32 vcc, v1, v102
	v_add_u32_e32 v1, 0xffffffad, v111
	s_nop 0
	v_cndmask_b32_e32 v38, v232, v38, vcc
	v_cmp_le_i32_e32 vcc, v1, v102
	v_add_u32_e32 v1, 0xffffff8e, v111
	s_nop 0
	v_cndmask_b32_e32 v54, v232, v54, vcc
	v_cmp_le_i32_e32 vcc, v1, v102
	v_add_u32_e32 v1, 0xffffffae, v111
	s_nop 0
	v_cndmask_b32_e32 v39, v232, v39, vcc
	v_cmp_le_i32_e32 vcc, v1, v102
	v_add_u32_e32 v1, 0xffffff8f, v111
	s_nop 0
	v_cndmask_b32_e32 v55, v232, v55, vcc
	v_cmp_le_i32_e32 vcc, v1, v102
	v_add_u32_e32 v1, 0xffffffaf, v111
	s_nop 0
	v_cndmask_b32_e32 v40, v232, v40, vcc
	v_cmp_le_i32_e32 vcc, v1, v102
	v_add_u32_e32 v1, 0xffffff90, v111
	s_nop 0
	v_cndmask_b32_e32 v56, v232, v56, vcc
	v_cmp_le_i32_e32 vcc, v1, v102
	v_add_u32_e32 v1, 0xffffffb0, v111
	s_nop 0
	v_cndmask_b32_e32 v41, v232, v41, vcc
	v_cmp_le_i32_e32 vcc, v1, v102
	v_add_u32_e32 v1, 0xffffff95, v111
	s_nop 0
	v_cndmask_b32_e32 v57, v232, v57, vcc
	v_cmp_le_i32_e32 vcc, v1, v102
	v_add_u32_e32 v1, 0xffffffb5, v111
	s_nop 0
	v_cndmask_b32_e32 v42, v232, v42, vcc
	v_cmp_le_i32_e32 vcc, v1, v102
	v_add_u32_e32 v1, 0xffffff96, v111
	s_nop 0
	v_cndmask_b32_e32 v58, v232, v58, vcc
	v_cmp_le_i32_e32 vcc, v1, v102
	v_add_u32_e32 v1, 0xffffffb6, v111
	s_nop 0
	v_cndmask_b32_e32 v43, v232, v43, vcc
	v_cmp_le_i32_e32 vcc, v1, v102
	v_add_u32_e32 v1, 0xffffff97, v111
	s_nop 0
	v_cndmask_b32_e32 v59, v232, v59, vcc
	v_cmp_le_i32_e32 vcc, v1, v102
	v_add_u32_e32 v1, 0xffffffb7, v111
	s_nop 0
	v_cndmask_b32_e32 v44, v232, v44, vcc
	v_cmp_le_i32_e32 vcc, v1, v102
	v_add_u32_e32 v1, 0xffffff98, v111
	s_nop 0
	v_cndmask_b32_e32 v60, v232, v60, vcc
	v_cmp_le_i32_e32 vcc, v1, v102
	v_add_u32_e32 v1, 0xffffffb8, v111
	s_nop 0
	v_cndmask_b32_e32 v45, v232, v45, vcc
	v_cmp_le_i32_e32 vcc, v1, v102
	v_add_u32_e32 v1, 0xffffff9d, v111
	s_nop 0
	v_cndmask_b32_e32 v61, v232, v61, vcc
	v_cmp_le_i32_e32 vcc, v1, v102
	v_add_u32_e32 v1, 0xffffffbd, v111
	s_nop 0
	v_cndmask_b32_e32 v46, v232, v46, vcc
	v_cmp_le_i32_e32 vcc, v1, v102
	v_add_u32_e32 v1, 0xffffff9e, v111
	s_nop 0
	v_cndmask_b32_e32 v62, v232, v62, vcc
	v_cmp_le_i32_e32 vcc, v1, v102
	v_add_u32_e32 v1, 0xffffffbe, v111
	s_nop 0
	v_cndmask_b32_e32 v47, v232, v47, vcc
	v_cmp_le_i32_e32 vcc, v1, v102
	v_add_u32_e32 v1, 0xffffff9f, v111
	s_nop 0
	v_cndmask_b32_e32 v63, v232, v63, vcc
	v_cmp_le_i32_e32 vcc, v1, v102
	v_add_u32_e32 v1, 0xffffffbf, v111
	s_nop 0
	v_cndmask_b32_e32 v48, v232, v48, vcc
	v_cmp_le_i32_e32 vcc, v1, v102
	v_add_u32_e32 v1, 0xffffffa0, v111
	s_nop 0
	v_cndmask_b32_e32 v64, v232, v64, vcc
	v_cmp_le_i32_e32 vcc, v1, v102
	v_subrev_u32_e32 v1, 64, v111
	s_nop 0
	v_cndmask_b32_e32 v49, v232, v49, vcc
	v_cmp_le_i32_e32 vcc, v1, v102
	s_nop 1
	v_cndmask_b32_e32 v65, v232, v65, vcc

; #define LAS __attribute__((address_space(3)))
; #define STAGE_TILE(bufi, KR, VR) do { LAS bf16_t* Ks_ = (LAS bf16_t*)(lds + (bufi) * 18432); LAS bf16_t* Vs_ = (LAS bf16_t*)(lds + (bufi) * 18432 + 9216); \
;         *(LAS u32x4*)(Ks_ + skr * 72 + sch * 8) = KR; *(LAS u32x4*)(Vs_ + skr * 72 + sch * 8) = VR; } while (0)
; #define LOAD_TILE(KR, VR, tl) do { KR = *(const GAS u32x4*)(kg + (size_t)(tl) * 64 * LDH); VR = *(const GAS u32x4*)(vg + (size_t)(tl) * 64 * LDH); } while (0)
; template <int MODE> ...
;     ...
;         STAGE_TILE(1, kB, vB);
;         __syncthreads();
;         if (MODE == 1) { const u32x4 fa = *(const LAS u32x4*)flags, fb = *(const LAS u32x4*)(flags + 4); if ((fa.x & fa.y & fa.z & fa.w & fb.x & fb.y & fb.z & fb.w) != 0u) break; }
;         LOAD_TILE(kB, vB, TILE_OF(min(it + 3, ntiles - 1)));
;         COMPUTE_TILE(TILE_OF(it + 1), 1);
.LBB0_832:
	s_add_i32 s4, s13, 3
	s_min_i32 s4, s4, s10
	v_mad_u64_u32 v[34:35], s[4:5], s4, v231, v[98:99]
	s_waitcnt vmcnt(3)
	ds_write_b128 v107, v[82:85] offset:18432
	s_waitcnt vmcnt(2)
	ds_write_b128 v107, v[86:89] offset:27648
	s_waitcnt lgkmcnt(0)
	s_barrier
	global_load_dwordx4 v[82:85], v[34:35], off offset:768
	global_load_dwordx4 v[86:89], v[34:35], off offset:1536
	s_cmp_ge_i32 s13, s9
	s_cbranch_scc1 .LBB0_840
	ds_read_b128 v[34:37], v110 offset:256
	ds_read_b128 v[38:41], v110 offset:288
	ds_read_b128 v[42:45], v110 offset:320
	ds_read_b128 v[46:49], v110 offset:352
	ds_read_b128 v[116:119], v113 offset:18432
	ds_read_b128 v[120:123], v113 offset:18464
	ds_read_b128 v[124:127], v113 offset:18496
	ds_read_b128 v[182:185], v113 offset:18528
	ds_read_b128 v[50:53], v110 offset:384
	ds_read_b128 v[54:57], v110 offset:416
	ds_read_b128 v[58:61], v110 offset:448
	ds_read_b128 v[62:65], v110 offset:480
	ds_read_b128 v[186:189], v113 offset:23040
	ds_read_b128 v[190:193], v113 offset:23072
	ds_read_b128 v[242:245], v113 offset:23104
	ds_read_b128 v[246:249], v113 offset:23136
	v_sub_f32_e32 v1, v105, v112
	s_waitcnt lgkmcnt(12)
	v_sub_f32_e32 v34, v1, v34
	v_sub_f32_e32 v35, v1, v35
	v_sub_f32_e32 v36, v1, v36
	v_sub_f32_e32 v37, v1, v37
	v_sub_f32_e32 v38, v1, v38
	v_sub_f32_e32 v39, v1, v39
	v_sub_f32_e32 v40, v1, v40
	v_sub_f32_e32 v41, v1, v41
	v_sub_f32_e32 v42, v1, v42
	v_sub_f32_e32 v43, v1, v43
	v_sub_f32_e32 v44, v1, v44
	v_sub_f32_e32 v45, v1, v45
	v_sub_f32_e32 v46, v1, v46
	v_sub_f32_e32 v47, v1, v47
	v_sub_f32_e32 v48, v1, v48
	v_sub_f32_e32 v49, v1, v49
	s_waitcnt lgkmcnt(4)
	v_mfma_f32_32x32x16_bf16 v[34:49], v[116:119], v[66:69], v[34:49]
	v_sub_f32_e32 v50, v1, v50
	v_sub_f32_e32 v51, v1, v51
	v_sub_f32_e32 v52, v1, v52
	v_sub_f32_e32 v53, v1, v53
	s_waitcnt lgkmcnt(4)
	v_mfma_f32_32x32x16_bf16 v[34:49], v[120:123], v[70:73], v[34:49]
	v_sub_f32_e32 v54, v1, v54
	v_sub_f32_e32 v55, v1, v55
	v_sub_f32_e32 v56, v1, v56
	v_sub_f32_e32 v57, v1, v57
	s_waitcnt lgkmcnt(4)
	v_mfma_f32_32x32x16_bf16 v[34:49], v[124:127], v[74:77], v[34:49]
	v_sub_f32_e32 v58, v1, v58
	v_sub_f32_e32 v59, v1, v59
	v_sub_f32_e32 v60, v1, v60
	v_sub_f32_e32 v61, v1, v61
	s_waitcnt lgkmcnt(0)
	v_mfma_f32_32x32x16_bf16 v[34:49], v[182:185], v[78:81], v[34:49]
	v_sub_f32_e32 v62, v1, v62
	v_sub_f32_e32 v63, v1, v63
	v_sub_f32_e32 v64, v1, v64
	v_sub_f32_e32 v65, v1, v65
	s_nop 1
	v_mfma_f32_32x32x16_bf16 v[50:65], v[186:189], v[66:69], v[50:65]
	ds_read_b64_tr_b16 v[198:199], v108 offset:27648
	ds_read_b64_tr_b16 v[200:201], v108 offset:28800
	ds_read_b64_tr_b16 v[202:203], v108 offset:29952
	ds_read_b64_tr_b16 v[204:205], v108 offset:31104
	v_mfma_f32_32x32x16_bf16 v[50:65], v[190:193], v[70:73], v[50:65]
	ds_read_b64_tr_b16 v[206:207], v108 offset:32256
	ds_read_b64_tr_b16 v[208:209], v108 offset:33408
	ds_read_b64_tr_b16 v[210:211], v108 offset:34560
	ds_read_b64_tr_b16 v[212:213], v108 offset:35712
	v_mfma_f32_32x32x16_bf16 v[50:65], v[242:245], v[74:77], v[50:65]
	ds_read_b64_tr_b16 v[214:215], v108 offset:27712
	ds_read_b64_tr_b16 v[216:217], v108 offset:28864
	ds_read_b64_tr_b16 v[218:219], v108 offset:30016
	ds_read_b64_tr_b16 v[220:221], v108 offset:31168
	v_mfma_f32_32x32x16_bf16 v[50:65], v[246:249], v[78:81], v[50:65]
	ds_read_b64_tr_b16 v[234:235], v108 offset:32320
	ds_read_b64_tr_b16 v[236:237], v108 offset:33472
	ds_read_b64_tr_b16 v[238:239], v108 offset:34624
	ds_read_b64_tr_b16 v[240:241], v108 offset:35776
	s_nop 1
	s_cmp_lg_u32 s11, s13
	s_cbranch_scc1 .LBB0_835
	v_subrev_u32_e32 v104, 27, v111
	v_subrev_u32_e32 v1, 59, v111
	v_cmp_le_i32_e32 vcc, v104, v102
	s_nop 7
	v_cndmask_b32_e32 v50, v232, v50, vcc
	v_cmp_lt_i32_e32 vcc, v1, v102
	s_nop 1
	v_cndmask_b32_e32 v35, v232, v35, vcc
	v_cmp_le_i32_e32 vcc, v1, v102
	v_subrev_u32_e32 v1, 26, v111
	s_nop 0
	v_cndmask_b32_e32 v34, v232, v34, vcc
	v_cmp_le_i32_e32 vcc, v1, v102
	v_subrev_u32_e32 v1, 57, v111
	s_nop 0
	v_cndmask_b32_e32 v51, v232, v51, vcc
	v_cmp_le_i32_e32 vcc, v1, v102
	v_subrev_u32_e32 v1, 25, v111
	s_nop 0
	v_cndmask_b32_e32 v36, v232, v36, vcc
	v_cmp_le_i32_e32 vcc, v1, v102
	v_subrev_u32_e32 v1, 56, v111
	s_nop 0
	v_cndmask_b32_e32 v52, v232, v52, vcc
	v_cmp_le_i32_e32 vcc, v1, v102
	v_subrev_u32_e32 v1, 24, v111
	s_nop 0
	v_cndmask_b32_e32 v37, v232, v37, vcc
	v_cmp_le_i32_e32 vcc, v1, v102
	v_subrev_u32_e32 v1, 51, v111
	s_nop 0
	v_cndmask_b32_e32 v53, v232, v53, vcc
	v_cmp_le_i32_e32 vcc, v1, v102
	v_subrev_u32_e32 v1, 19, v111
	s_nop 0
	v_cndmask_b32_e32 v38, v232, v38, vcc
	v_cmp_le_i32_e32 vcc, v1, v102
	v_subrev_u32_e32 v1, 50, v111
	s_nop 0
	v_cndmask_b32_e32 v54, v232, v54, vcc
	v_cmp_le_i32_e32 vcc, v1, v102
	v_subrev_u32_e32 v1, 18, v111
	s_nop 0
	v_cndmask_b32_e32 v39, v232, v39, vcc
	v_cmp_le_i32_e32 vcc, v1, v102
	v_subrev_u32_e32 v1, 49, v111
	s_nop 0
	v_cndmask_b32_e32 v55, v232, v55, vcc
	v_cmp_le_i32_e32 vcc, v1, v102
	v_subrev_u32_e32 v1, 17, v111
	s_nop 0
	v_cndmask_b32_e32 v40, v232, v40, vcc
	v_cmp_le_i32_e32 vcc, v1, v102
	v_subrev_u32_e32 v1, 48, v111
	s_nop 0
	v_cndmask_b32_e32 v56, v232, v56, vcc
	v_cmp_le_i32_e32 vcc, v1, v102
	v_add_u32_e32 v1, -16, v111
	s_nop 0
	v_cndmask_b32_e32 v41, v232, v41, vcc
	v_cmp_le_i32_e32 vcc, v1, v102
	v_subrev_u32_e32 v1, 43, v111
	s_nop 0
	v_cndmask_b32_e32 v57, v232, v57, vcc
	v_cmp_le_i32_e32 vcc, v1, v102
	v_add_u32_e32 v1, -11, v111
	s_nop 0
	v_cndmask_b32_e32 v42, v232, v42, vcc
	v_cmp_le_i32_e32 vcc, v1, v102
	v_subrev_u32_e32 v1, 42, v111
	s_nop 0
	v_cndmask_b32_e32 v58, v232, v58, vcc
	v_cmp_le_i32_e32 vcc, v1, v102
	v_add_u32_e32 v1, -10, v111
	s_nop 0
	v_cndmask_b32_e32 v43, v232, v43, vcc
	v_cmp_le_i32_e32 vcc, v1, v102
	v_subrev_u32_e32 v1, 41, v111
	s_nop 0
	v_cndmask_b32_e32 v59, v232, v59, vcc
	v_cmp_le_i32_e32 vcc, v1, v102
	v_add_u32_e32 v1, -9, v111
	s_nop 0
	v_cndmask_b32_e32 v44, v232, v44, vcc
	v_cmp_le_i32_e32 vcc, v1, v102
	v_subrev_u32_e32 v1, 40, v111
	s_nop 0
	v_cndmask_b32_e32 v60, v232, v60, vcc
	v_cmp_le_i32_e32 vcc, v1, v102
	v_add_u32_e32 v1, -8, v111
	s_nop 0
	v_cndmask_b32_e32 v45, v232, v45, vcc
	v_cmp_le_i32_e32 vcc, v1, v102
	v_subrev_u32_e32 v1, 35, v111
	s_nop 0
	v_cndmask_b32_e32 v61, v232, v61, vcc
	v_cmp_le_i32_e32 vcc, v1, v102
	v_add_u32_e32 v1, -3, v111
	s_nop 0
	v_cndmask_b32_e32 v46, v232, v46, vcc
	v_cmp_le_i32_e32 vcc, v1, v102
	v_subrev_u32_e32 v1, 34, v111
	s_nop 0
	v_cndmask_b32_e32 v62, v232, v62, vcc
	v_cmp_le_i32_e32 vcc, v1, v102
	v_add_u32_e32 v1, -2, v111
	s_nop 0
	v_cndmask_b32_e32 v47, v232, v47, vcc
	v_cmp_le_i32_e32 vcc, v1, v102
	v_subrev_u32_e32 v1, 33, v111
	s_nop 0
	v_cndmask_b32_e32 v63, v232, v63, vcc
	v_cmp_le_i32_e32 vcc, v1, v102
	v_add_u32_e32 v1, -1, v111
	s_nop 0
	v_cndmask_b32_e32 v48, v232, v48, vcc
	v_cmp_le_i32_e32 vcc, v1, v102
	v_subrev_u32_e32 v1, 32, v111
	s_nop 0
	v_cndmask_b32_e32 v64, v232, v64, vcc
	v_cmp_le_i32_e32 vcc, v1, v102
	s_nop 1
	v_cndmask_b32_e32 v49, v232, v49, vcc
	v_cmp_le_i32_e32 vcc, v111, v102
	s_nop 1
	v_cndmask_b32_e32 v65, v232, v65, vcc

.LBB0_920:
	s_add_i32 s19, s23, 2
	s_min_i32 s14, s19, s18
	v_mad_u64_u32 v[34:35], s[12:13], s14, v231, v[102:103]
	v_mad_u64_u32 v[36:37], s[12:13], s14, v231, v[104:105]
	global_load_dwordx4 v[90:93], v[34:35], off
	global_load_dwordx4 v[94:97], v[36:37], off
	s_cmp_gt_i32 s23, s17
	s_cbranch_scc1 .LBB0_926
	ds_read_b64 v[34:35], v109
	ds_read_b128 v[118:121], v113
	ds_read_b128 v[122:125], v113 offset:32
	ds_read_b128 v[126:129], v113 offset:64
	ds_read_b128 v[130:133], v113 offset:96
	ds_read_b128 v[182:185], v113 offset:4608
	ds_read_b128 v[186:189], v113 offset:4640
	ds_read_b128 v[190:193], v113 offset:4672
	ds_read_b128 v[242:245], v113 offset:4704
	v_sub_f32_e32 v1, 0, v112
	s_xor_b64 s[10:11], s[10:11], -1
	s_waitcnt lgkmcnt(8)
	v_lshrrev_b64 v[114:115], v100, v[34:35]
	v_lshrrev_b64 v[116:117], v106, v[34:35]
	v_bfe_i32 v34, v114, 0, 1
	v_bfe_i32 v35, v114, 1, 1
	v_bfe_i32 v36, v114, 2, 1
	v_bfe_i32 v37, v114, 3, 1
	v_bfe_i32 v38, v114, 8, 1
	v_bfe_i32 v39, v114, 9, 1
	v_bfe_i32 v40, v114, 10, 1
	v_bfe_i32 v41, v114, 11, 1
	v_bfe_i32 v42, v114, 16, 1
	v_bfe_i32 v43, v114, 17, 1
	v_bfe_i32 v44, v114, 18, 1
	v_bfe_i32 v45, v114, 19, 1
	v_bfe_i32 v46, v114, 24, 1
	v_bfe_i32 v47, v114, 25, 1
	v_bfe_i32 v48, v114, 26, 1
	v_bfe_i32 v49, v114, 27, 1
	v_bfi_b32 v34, v34, v1, v232
	v_bfi_b32 v35, v35, v1, v232
	v_bfi_b32 v36, v36, v1, v232
	v_bfi_b32 v37, v37, v1, v232
	v_bfi_b32 v38, v38, v1, v232
	v_bfi_b32 v39, v39, v1, v232
	v_bfi_b32 v40, v40, v1, v232
	v_bfi_b32 v41, v41, v1, v232
	v_bfi_b32 v42, v42, v1, v232
	v_bfi_b32 v43, v43, v1, v232
	v_bfi_b32 v44, v44, v1, v232
	v_bfi_b32 v45, v45, v1, v232
	v_bfi_b32 v46, v46, v1, v232
	v_bfi_b32 v47, v47, v1, v232
	v_bfi_b32 v48, v48, v1, v232
	v_bfi_b32 v49, v49, v1, v232
	s_waitcnt vmcnt(4) lgkmcnt(4)
	v_mfma_f32_32x32x16_bf16 v[34:49], v[118:121], v[74:77], v[34:49]
	v_bfe_i32 v50, v116, 0, 1
	v_bfe_i32 v51, v116, 1, 1
	v_bfe_i32 v52, v116, 2, 1
	v_bfe_i32 v53, v116, 3, 1
	v_bfe_i32 v54, v116, 8, 1
	v_bfe_i32 v55, v116, 9, 1
	v_bfe_i32 v56, v116, 10, 1
	v_bfe_i32 v57, v116, 11, 1
	s_waitcnt lgkmcnt(4)
	v_mfma_f32_32x32x16_bf16 v[34:49], v[122:125], v[66:69], v[34:49]
	v_bfe_i32 v58, v116, 16, 1
	v_bfe_i32 v59, v116, 17, 1
	v_bfe_i32 v60, v116, 18, 1
	v_bfe_i32 v61, v116, 19, 1
	v_bfe_i32 v62, v116, 24, 1
	v_bfe_i32 v63, v116, 25, 1
	v_bfe_i32 v64, v116, 26, 1
	v_bfe_i32 v65, v116, 27, 1
	s_waitcnt lgkmcnt(4)
	v_mfma_f32_32x32x16_bf16 v[34:49], v[126:129], v[70:73], v[34:49]
	v_bfi_b32 v50, v50, v1, v232
	v_bfi_b32 v51, v51, v1, v232
	v_bfi_b32 v52, v52, v1, v232
	v_bfi_b32 v53, v53, v1, v232
	v_bfi_b32 v54, v54, v1, v232
	v_bfi_b32 v55, v55, v1, v232
	v_bfi_b32 v56, v56, v1, v232
	v_bfi_b32 v57, v57, v1, v232
	s_waitcnt lgkmcnt(0)
	v_mfma_f32_32x32x16_bf16 v[34:49], v[130:133], v[78:81], v[34:49]
	v_bfi_b32 v58, v58, v1, v232
	v_bfi_b32 v59, v59, v1, v232
	v_bfi_b32 v60, v60, v1, v232
	v_bfi_b32 v61, v61, v1, v232
	v_bfi_b32 v62, v62, v1, v232
	v_bfi_b32 v63, v63, v1, v232
	v_bfi_b32 v64, v64, v1, v232
	v_bfi_b32 v65, v65, v1, v232
	s_nop 1
	v_mfma_f32_32x32x16_bf16 v[50:65], v[182:185], v[74:77], v[50:65]
	ds_read_b64_tr_b16 v[198:199], v107 offset:9216
	ds_read_b64_tr_b16 v[200:201], v107 offset:10368
	ds_read_b64_tr_b16 v[202:203], v107 offset:11520
	ds_read_b64_tr_b16 v[204:205], v107 offset:12672
	v_mfma_f32_32x32x16_bf16 v[50:65], v[186:189], v[66:69], v[50:65]
	ds_read_b64_tr_b16 v[206:207], v107 offset:13824
	ds_read_b64_tr_b16 v[208:209], v107 offset:14976
	ds_read_b64_tr_b16 v[210:211], v107 offset:16128
	ds_read_b64_tr_b16 v[212:213], v107 offset:17280
	v_mfma_f32_32x32x16_bf16 v[50:65], v[190:193], v[70:73], v[50:65]
	ds_read_b64_tr_b16 v[214:215], v107 offset:9280
	ds_read_b64_tr_b16 v[216:217], v107 offset:10432
	ds_read_b64_tr_b16 v[218:219], v107 offset:11584
	ds_read_b64_tr_b16 v[220:221], v107 offset:12736
	v_mfma_f32_32x32x16_bf16 v[50:65], v[242:245], v[78:81], v[50:65]
	ds_read_b64_tr_b16 v[234:235], v107 offset:13888
	ds_read_b64_tr_b16 v[236:237], v107 offset:15040
	ds_read_b64_tr_b16 v[238:239], v107 offset:16192
	ds_read_b64_tr_b16 v[240:241], v107 offset:17344
	s_nop 1
	v_max3_f32 v108, v34, v35, v36
	v_max3_f32 v110, v37, v38, v39
	v_max3_f32 v114, v40, v41, v42
	v_max3_f32 v1, v43, v44, v45
	v_max3_f32 v108, v108, v46, v47
	v_max3_f32 v110, v110, v48, v49
	v_max3_f32 v114, v114, v50, v51
	v_max3_f32 v1, v1, v52, v53
	v_max3_f32 v108, v108, v54, v55
	v_max3_f32 v110, v110, v56, v57
	v_max3_f32 v114, v114, v58, v59
	v_max3_f32 v1, v1, v60, v61
	v_max3_f32 v108, v108, v62, v63
	v_max3_f32 v110, v110, v64, v65
	v_max3_f32 v1, v1, v114, s82
	v_max3_f32 v1, v1, v108, v110
	v_and_b32_e32 v110, 64, v224
	v_xor_b32_e32 v108, 32, v224
	v_add_u32_e32 v110, 64, v110
	v_cmp_lt_i32_e32 vcc, v108, v110
	s_nop 1
	v_cndmask_b32_e32 v108, v224, v108, vcc
	v_lshlrev_b32_e32 v108, 2, v108
	ds_bpermute_b32 v108, v108, v1
	s_waitcnt lgkmcnt(0)
	v_max_f32_e32 v108, v108, v108
	v_max_f32_e32 v1, v1, v108
	s_and_saveexec_b64 s[12:13], s[10:11]
	s_xor_b64 s[10:11], exec, s[12:13]
	s_cbranch_execnz .LBB0_934
	s_or_saveexec_b64 s[12:13], s[10:11]
	s_mov_b64 s[10:11], 0
	s_xor_b64 exec, exec, s[12:13]
	s_cbranch_execnz .LBB0_937

; #define LAS __attribute__((address_space(3)))
; #define STAGE_TILE(bufi, KR, VR) do { LAS bf16_t* Ks_ = (LAS bf16_t*)(lds + (bufi) * 18432); LAS bf16_t* Vs_ = (LAS bf16_t*)(lds + (bufi) * 18432 + 9216); \
;         *(LAS u32x4*)(Ks_ + skr * 72 + sch * 8) = KR; *(LAS u32x4*)(Vs_ + skr * 72 + sch * 8) = VR; } while (0)
; #define LOAD_TILE(KR, VR, tl) do { KR = *(const GAS u32x4*)(kg + (size_t)(tl) * 64 * LDH); VR = *(const GAS u32x4*)(vg + (size_t)(tl) * 64 * LDH); } while (0)
; template <int MODE> ...
;     ...
;         STAGE_TILE(1, kB, vB);
;         __syncthreads();
;         if (MODE == 1) { const u32x4 fa = *(const LAS u32x4*)flags, fb = *(const LAS u32x4*)(flags + 4); if ((fa.x & fa.y & fa.z & fa.w & fb.x & fb.y & fb.z & fb.w) != 0u) break; }
;         LOAD_TILE(kB, vB, TILE_OF(min(it + 3, ntiles - 1)));
;         COMPUTE_TILE(TILE_OF(it + 1), 1);
.LBB0_926:
	s_add_i32 s12, s23, 3
	s_min_i32 s14, s12, s18
	v_mad_u64_u32 v[34:35], s[12:13], s14, v231, v[102:103]
	s_waitcnt vmcnt(3)
	ds_write_b128 v101, v[82:85] offset:18432
	s_waitcnt vmcnt(2)
	ds_write_b128 v101, v[86:89] offset:27648
	s_waitcnt lgkmcnt(0)
	s_barrier
	v_mad_u64_u32 v[36:37], s[12:13], s14, v231, v[104:105]
	global_load_dwordx4 v[82:85], v[34:35], off
	global_load_dwordx4 v[86:89], v[36:37], off
	s_cmp_ge_i32 s23, s17
	s_cbranch_scc1 .LBB0_932
	ds_read_b64 v[34:35], v109 offset:8
	ds_read_b128 v[118:121], v113 offset:18432
	ds_read_b128 v[122:125], v113 offset:18464
	ds_read_b128 v[126:129], v113 offset:18496
	ds_read_b128 v[130:133], v113 offset:18528
	ds_read_b128 v[182:185], v113 offset:23040
	ds_read_b128 v[186:189], v113 offset:23072
	ds_read_b128 v[190:193], v113 offset:23104
	ds_read_b128 v[242:245], v113 offset:23136
	v_sub_f32_e32 v1, 0, v112
	s_xor_b64 s[10:11], s[10:11], -1
	s_waitcnt lgkmcnt(8)
	v_lshrrev_b64 v[114:115], v100, v[34:35]
	v_lshrrev_b64 v[116:117], v106, v[34:35]
	v_bfe_i32 v34, v114, 0, 1
	v_bfe_i32 v35, v114, 1, 1
	v_bfe_i32 v36, v114, 2, 1
	v_bfe_i32 v37, v114, 3, 1
	v_bfe_i32 v38, v114, 8, 1
	v_bfe_i32 v39, v114, 9, 1
	v_bfe_i32 v40, v114, 10, 1
	v_bfe_i32 v41, v114, 11, 1
	v_bfe_i32 v42, v114, 16, 1
	v_bfe_i32 v43, v114, 17, 1
	v_bfe_i32 v44, v114, 18, 1
	v_bfe_i32 v45, v114, 19, 1
	v_bfe_i32 v46, v114, 24, 1
	v_bfe_i32 v47, v114, 25, 1
	v_bfe_i32 v48, v114, 26, 1
	v_bfe_i32 v49, v114, 27, 1
	v_bfi_b32 v34, v34, v1, v232
	v_bfi_b32 v35, v35, v1, v232
	v_bfi_b32 v36, v36, v1, v232
	v_bfi_b32 v37, v37, v1, v232
	v_bfi_b32 v38, v38, v1, v232
	v_bfi_b32 v39, v39, v1, v232
	v_bfi_b32 v40, v40, v1, v232
	v_bfi_b32 v41, v41, v1, v232
	v_bfi_b32 v42, v42, v1, v232
	v_bfi_b32 v43, v43, v1, v232
	v_bfi_b32 v44, v44, v1, v232
	v_bfi_b32 v45, v45, v1, v232
	v_bfi_b32 v46, v46, v1, v232
	v_bfi_b32 v47, v47, v1, v232
	v_bfi_b32 v48, v48, v1, v232
	v_bfi_b32 v49, v49, v1, v232
	s_waitcnt lgkmcnt(4)
	v_mfma_f32_32x32x16_bf16 v[34:49], v[118:121], v[74:77], v[34:49]
	v_bfe_i32 v50, v116, 0, 1
	v_bfe_i32 v51, v116, 1, 1
	v_bfe_i32 v52, v116, 2, 1
	v_bfe_i32 v53, v116, 3, 1
	v_bfe_i32 v54, v116, 8, 1
	v_bfe_i32 v55, v116, 9, 1
	v_bfe_i32 v56, v116, 10, 1
	v_bfe_i32 v57, v116, 11, 1
	s_waitcnt lgkmcnt(4)
	v_mfma_f32_32x32x16_bf16 v[34:49], v[122:125], v[66:69], v[34:49]
	v_bfe_i32 v58, v116, 16, 1
	v_bfe_i32 v59, v116, 17, 1
	v_bfe_i32 v60, v116, 18, 1
	v_bfe_i32 v61, v116, 19, 1
	v_bfe_i32 v62, v116, 24, 1
	v_bfe_i32 v63, v116, 25, 1
	v_bfe_i32 v64, v116, 26, 1
	v_bfe_i32 v65, v116, 27, 1
	s_waitcnt lgkmcnt(4)
	v_mfma_f32_32x32x16_bf16 v[34:49], v[126:129], v[70:73], v[34:49]
	v_bfi_b32 v50, v50, v1, v232
	v_bfi_b32 v51, v51, v1, v232
	v_bfi_b32 v52, v52, v1, v232
	v_bfi_b32 v53, v53, v1, v232
	v_bfi_b32 v54, v54, v1, v232
	v_bfi_b32 v55, v55, v1, v232
	v_bfi_b32 v56, v56, v1, v232
	v_bfi_b32 v57, v57, v1, v232
	s_waitcnt lgkmcnt(0)
	v_mfma_f32_32x32x16_bf16 v[34:49], v[130:133], v[78:81], v[34:49]
	v_bfi_b32 v58, v58, v1, v232
	v_bfi_b32 v59, v59, v1, v232
	v_bfi_b32 v60, v60, v1, v232
	v_bfi_b32 v61, v61, v1, v232
	v_bfi_b32 v62, v62, v1, v232
	v_bfi_b32 v63, v63, v1, v232
	v_bfi_b32 v64, v64, v1, v232
	v_bfi_b32 v65, v65, v1, v232
	s_nop 1
	v_mfma_f32_32x32x16_bf16 v[50:65], v[182:185], v[74:77], v[50:65]
	ds_read_b64_tr_b16 v[198:199], v107 offset:27648
	ds_read_b64_tr_b16 v[200:201], v107 offset:28800
	ds_read_b64_tr_b16 v[202:203], v107 offset:29952
	ds_read_b64_tr_b16 v[204:205], v107 offset:31104
	v_mfma_f32_32x32x16_bf16 v[50:65], v[186:189], v[66:69], v[50:65]
	ds_read_b64_tr_b16 v[206:207], v107 offset:32256
	ds_read_b64_tr_b16 v[208:209], v107 offset:33408
	ds_read_b64_tr_b16 v[210:211], v107 offset:34560
	ds_read_b64_tr_b16 v[212:213], v107 offset:35712
	v_mfma_f32_32x32x16_bf16 v[50:65], v[190:193], v[70:73], v[50:65]
	ds_read_b64_tr_b16 v[214:215], v107 offset:27712
	ds_read_b64_tr_b16 v[216:217], v107 offset:28864
	ds_read_b64_tr_b16 v[218:219], v107 offset:30016
	ds_read_b64_tr_b16 v[220:221], v107 offset:31168
	v_mfma_f32_32x32x16_bf16 v[50:65], v[242:245], v[78:81], v[50:65]
	ds_read_b64_tr_b16 v[234:235], v107 offset:32320
	ds_read_b64_tr_b16 v[236:237], v107 offset:33472
	ds_read_b64_tr_b16 v[238:239], v107 offset:34624
	ds_read_b64_tr_b16 v[240:241], v107 offset:35776
	s_nop 1
	v_max3_f32 v108, v34, v35, v36
	v_max3_f32 v110, v37, v38, v39
	v_max3_f32 v114, v40, v41, v42
	v_max3_f32 v1, v43, v44, v45
	v_max3_f32 v108, v108, v46, v47
	v_max3_f32 v110, v110, v48, v49
	v_max3_f32 v114, v114, v50, v51
	v_max3_f32 v1, v1, v52, v53
	v_max3_f32 v108, v108, v54, v55
	v_max3_f32 v110, v110, v56, v57
	v_max3_f32 v114, v114, v58, v59
	v_max3_f32 v1, v1, v60, v61
	v_max3_f32 v108, v108, v62, v63
	v_max3_f32 v110, v110, v64, v65
	v_max3_f32 v1, v1, v114, s82
	v_max3_f32 v1, v1, v108, v110
	v_and_b32_e32 v110, 64, v224
	v_xor_b32_e32 v108, 32, v224
	v_add_u32_e32 v110, 64, v110
	v_cmp_lt_i32_e32 vcc, v108, v110
	s_nop 1
	v_cndmask_b32_e32 v108, v224, v108, vcc
	v_lshlrev_b32_e32 v108, 2, v108
	ds_bpermute_b32 v108, v108, v1
	s_waitcnt lgkmcnt(0)
	v_max_f32_e32 v108, v108, v108
	v_max_f32_e32 v1, v1, v108
	s_and_saveexec_b64 s[12:13], s[10:11]
	s_xor_b64 s[10:11], exec, s[12:13]
	s_cbranch_execnz .LBB0_940
	s_or_saveexec_b64 s[12:13], s[10:11]
	s_mov_b64 s[10:11], 0
	s_xor_b64 exec, exec, s[12:13]
	s_cbranch_execnz .LBB0_943
